# scan consumer loop: v_pk f32 ops split into scalar pairs
# baseline (speedup 1.0000x reference)
; __device__ __forceinline__ void scan_phase(const Args& a, LAS unsigned char* lds, const bf16* Z, const float* W, const bf16* Aa, const bf16* KK, float* Y, int tid, int lane, int wave) {
;     ...
;             if (consumer) {
;                 const LAS float* sb = buf + (ch & 1) * (SCH * SROW) + 4 * j;
;                 const LAS float* vb = buf + (ch & 1) * (SCH * SROW) + 320 + ri;
;                 f32x4 pw[3], pk[3], pa[3], pb[3], pr[3]; float pv[3];
; #pragma unroll
;                 for (int i = 0; i < 2; ++i) { const LAS float* p = sb + i * SROW;
;                     pw[i] = *(const LAS f32x4*)p; pk[i] = *(const LAS f32x4*)(p + 64); pa[i] = *(const LAS f32x4*)(p + 128); pb[i] = *(const LAS f32x4*)(p + 192); pr[i] = *(const LAS f32x4*)(p + 256); pv[i] = vb[i * SROW]; }
;                 float ykA = 0.f, ykB = 0.f, yd = 0.f;
; #pragma unroll
;                 for (int q = 0; q < SCH; ++q) {
;                     const f32x4 wv = pw[q % 3], kv = pk[q % 3], av = pa[q % 3], bv = pb[q % 3], rv = pr[q % 3]; const float vv = pv[q % 3];
;                     if (q + 2 < SCH) {
;                         const LAS float* p = sb + (q + 2) * SROW; const int i = (q + 2) % 3;
;                         pw[i] = *(const LAS f32x4*)p; pk[i] = *(const LAS f32x4*)(p + 64); pa[i] = *(const LAS f32x4*)(p + 128); pb[i] = *(const LAS f32x4*)(p + 192); pr[i] = *(const LAS f32x4*)(p + 256);
;                         pv[i] = vb[(q + 2) * SROW];
;                     }
;                     f32x2 t2 = S01 * (f32x2){av.x, av.y}; t2 = S23 * (f32x2){av.z, av.w} + t2;
;                     float sa = t2.x + t2.y;
;                     sa += dppf<0xB1>(sa); yd += dppf<0xB1>(yd);
;                     sa += dppf<0x4E>(sa); yd += dppf<0x4E>(yd);
;                     sa += dppf<0x141>(sa); yd += dppf<0x141>(yd);
;                     sa += dppf<0x140>(sa); yd += dppf<0x140>(yd);
;                     if (q > 0) { if (q <= 16) ykA = (j == q - 1) ? yd : ykA; else ykB = (j == q - 17) ? yd : ykB; }
;                     const f32x2 u01 = S01 * (f32x2){wv.x, wv.y} + (f32x2){kv.x, kv.y} * vv, u23 = S23 * (f32x2){wv.z, wv.w} + (f32x2){kv.z, kv.w} * vv;
;                     S01 = u01 + (f32x2){bv.x, bv.y} * sa; S23 = u23 + (f32x2){bv.z, bv.w} * sa;
;                     f32x2 y2 = S01 * (f32x2){rv.x, rv.y}; y2 = S23 * (f32x2){rv.z, rv.w} + y2;
;                     yd = y2.x + y2.y;
.LBB0_283:
	s_andn2_b64 vcc, exec, s[12:13]
	s_cbranch_vccnz .LBB0_224
	s_bitcmp1_b32 s22, 0
	s_cselect_b32 s16, 0xa800, 0
	s_add_i32 s16, s16, 0
	v_add_u32_e32 v195, s16, v123
	v_lshl_add_u32 v127, v126, 2, s16
	ds_read_b128 v[62:65], v195
	ds_read_b128 v[66:69], v195 offset:256
	ds_read_b128 v[70:73], v195 offset:512
	ds_read_b128 v[74:77], v195 offset:768
	ds_read_b128 v[78:81], v195 offset:1024
	ds_read_b32 v0, v127 offset:1280
	ds_read_b128 v[98:101], v195 offset:1344
	ds_read_b128 v[102:105], v195 offset:1600
	ds_read_b128 v[106:109], v195 offset:1856
	ds_read_b128 v[110:113], v195 offset:2112
	ds_read_b128 v[114:117], v195 offset:2368
	ds_read_b32 v182, v127 offset:2624
	ds_read_b128 v[184:187], v195 offset:2688
	ds_read_b128 v[196:199], v195 offset:2944
	ds_read_b128 v[200:203], v195 offset:3200
	ds_read_b128 v[204:207], v195 offset:3456
	ds_read_b128 v[208:211], v195 offset:3712
	ds_read_b32 v188, v127 offset:3968
	s_waitcnt lgkmcnt(14)
	v_mul_f32_e32 v70, v58, v70
	v_mul_f32_e32 v71, v59, v71
	s_waitcnt lgkmcnt(12)
	v_mul_f32_e32 v66, v66, v0
	v_mul_f32_e32 v67, v67, v0
	v_fmac_f32_e32 v70, v60, v72
	v_fmac_f32_e32 v71, v61, v73
	v_fma_f32 v58, v58, v62, v66
	v_fma_f32 v59, v59, v63, v67
	v_add_f32_e32 v70, v70, v71
	v_mul_f32_e32 v62, v68, v0
	v_mul_f32_e32 v63, v69, v0
	s_nop 0
	v_add_f32_dpp v70, v70, v70 quad_perm:[1,0,3,2] row_mask:0xf bank_mask:0xf bound_ctrl:1
	v_fma_f32 v60, v60, v64, v62
	v_fma_f32 v61, v61, v65, v63
	s_nop 0
	v_add_f32_dpp v70, v70, v70 quad_perm:[2,3,0,1] row_mask:0xf bank_mask:0xf bound_ctrl:1
	s_nop 1
	v_add_f32_dpp v70, v70, v70 row_half_mirror row_mask:0xf bank_mask:0xf bound_ctrl:1
	s_nop 1
	v_add_f32_dpp v70, v70, v70 row_mirror row_mask:0xf bank_mask:0xf bound_ctrl:1
	v_fmac_f32_e32 v58, v74, v70
	v_fmac_f32_e32 v59, v75, v70
	v_fmac_f32_e32 v60, v76, v70
	v_fmac_f32_e32 v61, v77, v70
	v_mul_f32_e32 v62, v78, v58
	v_mul_f32_e32 v63, v79, v59
	s_nop 0
	v_fmac_f32_e32 v62, v80, v60
	v_fmac_f32_e32 v63, v81, v61
	ds_read_b128 v[82:85], v195 offset:4032
	ds_read_b128 v[86:89], v195 offset:4288
	ds_read_b128 v[94:97], v195 offset:4544
	ds_read_b128 v[90:93], v195 offset:4800
	ds_read_b128 v[78:81], v195 offset:5056
	ds_read_b32 v212, v127 offset:5312
	v_add_f32_e32 v0, v62, v63
	s_waitcnt lgkmcnt(14)
	v_mul_f32_e32 v62, v106, v58
	v_mul_f32_e32 v63, v107, v59
	v_mul_f32_e32 v58, v98, v58
	v_mul_f32_e32 v59, v99, v59
	v_fmac_f32_e32 v62, v108, v60
	v_fmac_f32_e32 v63, v109, v61
	v_add_f32_dpp v0, v0, v0 quad_perm:[1,0,3,2] row_mask:0xf bank_mask:0xf bound_ctrl:1
	v_add_f32_e32 v62, v62, v63
	s_waitcnt lgkmcnt(12)
	v_fmac_f32_e32 v58, v102, v182
	v_fmac_f32_e32 v59, v103, v182
	v_add_f32_dpp v0, v0, v0 quad_perm:[2,3,0,1] row_mask:0xf bank_mask:0xf bound_ctrl:1
	v_add_f32_dpp v62, v62, v62 quad_perm:[1,0,3,2] row_mask:0xf bank_mask:0xf bound_ctrl:1
	v_mul_f32_e32 v60, v100, v60
	v_mul_f32_e32 v61, v101, v61
	v_add_f32_dpp v63, v0, v0 row_half_mirror row_mask:0xf bank_mask:0xf bound_ctrl:1
	v_add_f32_dpp v62, v62, v62 quad_perm:[2,3,0,1] row_mask:0xf bank_mask:0xf bound_ctrl:1
	v_fmac_f32_e32 v60, v104, v182
	v_fmac_f32_e32 v61, v105, v182
	s_nop 0
	v_add_f32_dpp v62, v62, v62 row_half_mirror row_mask:0xf bank_mask:0xf bound_ctrl:1
	s_nop 1
	v_add_f32_dpp v0, v62, v62 row_mirror row_mask:0xf bank_mask:0xf bound_ctrl:1
	v_add_f32_dpp v62, v63, v63 row_mirror row_mask:0xf bank_mask:0xf bound_ctrl:1
	v_fmac_f32_e32 v58, v110, v0
	v_fmac_f32_e32 v59, v111, v0
	v_cndmask_b32_e64 v64, 0, v62, s[82:83]
	v_fmac_f32_e32 v60, v112, v0
	v_fmac_f32_e32 v61, v113, v0
	v_mul_f32_e32 v62, v114, v58
	v_mul_f32_e32 v63, v115, v59
	s_nop 0
	v_fmac_f32_e32 v62, v116, v60
	v_fmac_f32_e32 v63, v117, v61
	ds_read_b128 v[102:105], v195 offset:5376
	ds_read_b128 v[106:109], v195 offset:5632
	ds_read_b128 v[114:117], v195 offset:5888
	ds_read_b128 v[110:113], v195 offset:6144
	ds_read_b128 v[98:101], v195 offset:6400
	ds_read_b32 v214, v127 offset:6656
	v_add_f32_e32 v0, v62, v63
	s_waitcnt lgkmcnt(14)
	v_mul_f32_e32 v62, v200, v58
	v_mul_f32_e32 v63, v201, v59
	v_mul_f32_e32 v58, v184, v58
	v_mul_f32_e32 v59, v185, v59
	v_fmac_f32_e32 v62, v202, v60
	v_fmac_f32_e32 v63, v203, v61
	v_add_f32_dpp v0, v0, v0 quad_perm:[1,0,3,2] row_mask:0xf bank_mask:0xf bound_ctrl:1
	v_add_f32_e32 v62, v62, v63
	s_waitcnt lgkmcnt(12)
	v_fmac_f32_e32 v58, v196, v188
	v_fmac_f32_e32 v59, v197, v188
	v_add_f32_dpp v0, v0, v0 quad_perm:[2,3,0,1] row_mask:0xf bank_mask:0xf bound_ctrl:1
	v_add_f32_dpp v62, v62, v62 quad_perm:[1,0,3,2] row_mask:0xf bank_mask:0xf bound_ctrl:1
	v_mul_f32_e32 v60, v186, v60
	v_mul_f32_e32 v61, v187, v61
	v_add_f32_dpp v63, v0, v0 row_half_mirror row_mask:0xf bank_mask:0xf bound_ctrl:1
	v_add_f32_dpp v62, v62, v62 quad_perm:[2,3,0,1] row_mask:0xf bank_mask:0xf bound_ctrl:1
	v_fmac_f32_e32 v60, v198, v188
	v_fmac_f32_e32 v61, v199, v188
	s_nop 0
	v_add_f32_dpp v62, v62, v62 row_half_mirror row_mask:0xf bank_mask:0xf bound_ctrl:1
	s_nop 1
	v_add_f32_dpp v0, v62, v62 row_mirror row_mask:0xf bank_mask:0xf bound_ctrl:1
	v_fma_f32 v184, v204, v0, v58
	v_fma_f32 v185, v205, v0, v59
	v_fma_f32 v186, v206, v0, v60
	v_fma_f32 v187, v207, v0, v61
	v_mul_f32_e32 v58, v208, v184
	v_mul_f32_e32 v59, v209, v185
	s_waitcnt lgkmcnt(9)
	v_mul_f32_e32 v94, v94, v184
	v_mul_f32_e32 v95, v95, v185
	v_fmac_f32_e32 v58, v210, v186
	v_fmac_f32_e32 v59, v211, v187
	v_fmac_f32_e32 v94, v96, v186
	v_fmac_f32_e32 v95, v97, v187
	v_add_f32_e32 v188, v58, v59
	v_add_f32_e32 v94, v94, v95
	v_mul_f32_e32 v82, v82, v184
	v_mul_f32_e32 v83, v83, v185
	v_add_f32_dpp v95, v188, v188 quad_perm:[1,0,3,2] row_mask:0xf bank_mask:0xf bound_ctrl:1
	v_add_f32_dpp v94, v94, v94 quad_perm:[1,0,3,2] row_mask:0xf bank_mask:0xf bound_ctrl:1
	s_waitcnt lgkmcnt(6)
; #define LAS __attribute__((address_space(3)))
; template <int CTRL> __device__ __forceinline__ float dppf(float v) { return __int_as_float(__builtin_amdgcn_update_dpp(0, __float_as_int(v), CTRL, 0xf, 0xf, true)); }
; __device__ __forceinline__ void scan_phase(const Args& a, LAS unsigned char* lds, const bf16* Z, const float* W, const bf16* Aa, const bf16* KK, float* Y, int tid, int lane, int wave) {
;     ...
;                 for (int q = 0; q < SCH; ++q) {
;                     const f32x4 wv = pw[q % 3], kv = pk[q % 3], av = pa[q % 3], bv = pb[q % 3], rv = pr[q % 3]; const float vv = pv[q % 3];
;                     if (q + 2 < SCH) {
;                         const LAS float* p = sb + (q + 2) * SROW; const int i = (q + 2) % 3;
;                         pw[i] = *(const LAS f32x4*)p; pk[i] = *(const LAS f32x4*)(p + 64); pa[i] = *(const LAS f32x4*)(p + 128); pb[i] = *(const LAS f32x4*)(p + 192); pr[i] = *(const LAS f32x4*)(p + 256);
;                         pv[i] = vb[(q + 2) * SROW];
;                     }
;                     f32x2 t2 = S01 * (f32x2){av.x, av.y}; t2 = S23 * (f32x2){av.z, av.w} + t2;
;                     float sa = t2.x + t2.y;
;                     sa += dppf<0xB1>(sa); yd += dppf<0xB1>(yd);
;                     sa += dppf<0x4E>(sa); yd += dppf<0x4E>(yd);
;                     sa += dppf<0x141>(sa); yd += dppf<0x141>(yd);
;                     sa += dppf<0x140>(sa); yd += dppf<0x140>(yd);
;                     if (q > 0) { if (q <= 16) ykA = (j == q - 1) ? yd : ykA; else ykB = (j == q - 17) ? yd : ykB; }
;                     const f32x2 u01 = S01 * (f32x2){wv.x, wv.y} + (f32x2){kv.x, kv.y} * vv, u23 = S23 * (f32x2){wv.z, wv.w} + (f32x2){kv.z, kv.w} * vv;
;                     S01 = u01 + (f32x2){bv.x, bv.y} * sa; S23 = u23 + (f32x2){bv.z, bv.w} * sa;
;                     f32x2 y2 = S01 * (f32x2){rv.x, rv.y}; y2 = S23 * (f32x2){rv.z, rv.w} + y2;
;                     yd = y2.x + y2.y;
;                 }
	v_fmac_f32_e32 v82, v86, v212
	v_fmac_f32_e32 v83, v87, v212
	v_add_f32_dpp v95, v95, v95 quad_perm:[2,3,0,1] row_mask:0xf bank_mask:0xf bound_ctrl:1
	v_add_f32_dpp v94, v94, v94 quad_perm:[2,3,0,1] row_mask:0xf bank_mask:0xf bound_ctrl:1
	v_mul_f32_e32 v84, v84, v186
	v_mul_f32_e32 v85, v85, v187
	v_add_f32_dpp v95, v95, v95 row_half_mirror row_mask:0xf bank_mask:0xf bound_ctrl:1
	v_add_f32_dpp v94, v94, v94 row_half_mirror row_mask:0xf bank_mask:0xf bound_ctrl:1
	v_fmac_f32_e32 v84, v88, v212
	v_fmac_f32_e32 v85, v89, v212
	v_add_f32_dpp v95, v95, v95 row_mirror row_mask:0xf bank_mask:0xf bound_ctrl:1
	v_add_f32_dpp v94, v94, v94 row_mirror row_mask:0xf bank_mask:0xf bound_ctrl:1
	v_fma_f32 v184, v90, v94, v82
	v_fma_f32 v185, v91, v94, v83
	v_fma_f32 v186, v92, v94, v84
	v_fma_f32 v187, v93, v94, v85
	v_mul_f32_e32 v78, v78, v184
	v_mul_f32_e32 v79, v79, v185
	s_waitcnt lgkmcnt(3)
	v_mul_f32_e32 v114, v114, v184
	v_mul_f32_e32 v115, v115, v185
	v_fmac_f32_e32 v78, v80, v186
	v_fmac_f32_e32 v79, v81, v187
	v_fmac_f32_e32 v114, v116, v186
	v_fmac_f32_e32 v115, v117, v187
	v_add_f32_e32 v196, v78, v79
	v_add_f32_e32 v114, v114, v115
	v_add_f32_dpp v62, v63, v63 row_mirror row_mask:0xf bank_mask:0xf bound_ctrl:1
	v_add_f32_dpp v115, v196, v196 quad_perm:[1,0,3,2] row_mask:0xf bank_mask:0xf bound_ctrl:1
	v_add_f32_dpp v114, v114, v114 quad_perm:[1,0,3,2] row_mask:0xf bank_mask:0xf bound_ctrl:1
	v_mul_f32_e32 v102, v102, v184
	v_mul_f32_e32 v103, v103, v185
	v_add_f32_dpp v115, v115, v115 quad_perm:[2,3,0,1] row_mask:0xf bank_mask:0xf bound_ctrl:1
	v_add_f32_dpp v114, v114, v114 quad_perm:[2,3,0,1] row_mask:0xf bank_mask:0xf bound_ctrl:1
	v_cndmask_b32_e64 v182, v64, v62, s[80:81]
	v_add_f32_dpp v115, v115, v115 row_half_mirror row_mask:0xf bank_mask:0xf bound_ctrl:1
	v_add_f32_dpp v114, v114, v114 row_half_mirror row_mask:0xf bank_mask:0xf bound_ctrl:1
	ds_read_b128 v[70:73], v195 offset:6720
	ds_read_b128 v[66:69], v195 offset:6976
	ds_read_b128 v[74:77], v195 offset:7232
	ds_read_b128 v[62:65], v195 offset:7488
	ds_read_b128 v[58:61], v195 offset:7744
	ds_read_b32 v0, v127 offset:8000
	v_add_f32_dpp v114, v114, v114 row_mirror row_mask:0xf bank_mask:0xf bound_ctrl:1
	v_add_f32_dpp v115, v115, v115 row_mirror row_mask:0xf bank_mask:0xf bound_ctrl:1
	s_waitcnt lgkmcnt(6)
	v_fmac_f32_e32 v102, v106, v214
	v_fmac_f32_e32 v103, v107, v214
	v_mul_f32_e32 v104, v104, v186
	v_mul_f32_e32 v105, v105, v187
	v_fma_f32 v186, v110, v114, v102
	v_fma_f32 v187, v111, v114, v103
	v_fmac_f32_e32 v104, v108, v214
	v_fmac_f32_e32 v105, v109, v214
	v_mul_f32_e32 v98, v98, v186
	v_mul_f32_e32 v99, v99, v187
	v_fma_f32 v184, v112, v114, v104
	v_fma_f32 v185, v113, v114, v105
	s_waitcnt lgkmcnt(3)
	v_mul_f32_e32 v74, v74, v186
	v_mul_f32_e32 v75, v75, v187
	v_fmac_f32_e32 v98, v100, v184
	v_fmac_f32_e32 v99, v101, v185
	v_fmac_f32_e32 v74, v76, v184
	v_fmac_f32_e32 v75, v77, v185
	v_add_f32_e32 v197, v98, v99
	v_add_f32_e32 v74, v74, v75
	v_mul_f32_e32 v70, v70, v186
	v_mul_f32_e32 v71, v71, v187
	v_add_f32_dpp v75, v197, v197 quad_perm:[1,0,3,2] row_mask:0xf bank_mask:0xf bound_ctrl:1
	v_add_f32_dpp v74, v74, v74 quad_perm:[1,0,3,2] row_mask:0xf bank_mask:0xf bound_ctrl:1
	s_waitcnt lgkmcnt(0)
	v_fma_f32 v66, v66, v0, v70
	v_fma_f32 v67, v67, v0, v71
	v_add_f32_dpp v75, v75, v75 quad_perm:[2,3,0,1] row_mask:0xf bank_mask:0xf bound_ctrl:1
	v_add_f32_dpp v74, v74, v74 quad_perm:[2,3,0,1] row_mask:0xf bank_mask:0xf bound_ctrl:1
	v_mul_f32_e32 v70, v72, v184
	v_mul_f32_e32 v71, v73, v185
	v_add_f32_dpp v75, v75, v75 row_half_mirror row_mask:0xf bank_mask:0xf bound_ctrl:1
	v_add_f32_dpp v74, v74, v74 row_half_mirror row_mask:0xf bank_mask:0xf bound_ctrl:1
	v_cndmask_b32_e64 v188, v182, v95, s[6:7]
	v_add_f32_dpp v75, v75, v75 row_mirror row_mask:0xf bank_mask:0xf bound_ctrl:1
	v_add_f32_dpp v74, v74, v74 row_mirror row_mask:0xf bank_mask:0xf bound_ctrl:1
	ds_read_b128 v[90:93], v195 offset:8064
	ds_read_b128 v[86:89], v195 offset:8320
	ds_read_b128 v[94:97], v195 offset:8576
	ds_read_b128 v[82:85], v195 offset:8832
	ds_read_b128 v[78:81], v195 offset:9088
	ds_read_b32 v182, v127 offset:9344
	v_fma_f32 v68, v68, v0, v70
	v_fma_f32 v69, v69, v0, v71
	v_fma_f32 v184, v62, v74, v66
	v_fma_f32 v185, v63, v74, v67
	v_fma_f32 v186, v64, v74, v68
	v_fma_f32 v187, v65, v74, v69
	v_mul_f32_e32 v58, v58, v184
	v_mul_f32_e32 v59, v59, v185
	s_waitcnt lgkmcnt(3)
	v_mul_f32_e32 v94, v94, v184
	v_mul_f32_e32 v95, v95, v185
	v_fmac_f32_e32 v58, v60, v186
	v_fmac_f32_e32 v59, v61, v187
	v_fmac_f32_e32 v94, v96, v186
	v_fmac_f32_e32 v95, v97, v187
	v_add_f32_e32 v197, v58, v59
	v_add_f32_e32 v94, v94, v95
	v_cndmask_b32_e64 v196, v188, v115, s[8:9]
	v_add_f32_dpp v95, v197, v197 quad_perm:[1,0,3,2] row_mask:0xf bank_mask:0xf bound_ctrl:1
	v_add_f32_dpp v94, v94, v94 quad_perm:[1,0,3,2] row_mask:0xf bank_mask:0xf bound_ctrl:1
	v_cndmask_b32_e64 v196, v196, v75, s[10:11]
	v_add_f32_dpp v95, v95, v95 quad_perm:[2,3,0,1] row_mask:0xf bank_mask:0xf bound_ctrl:1
	v_add_f32_dpp v94, v94, v94 quad_perm:[2,3,0,1] row_mask:0xf bank_mask:0xf bound_ctrl:1
	v_mul_f32_e32 v90, v90, v184
	v_mul_f32_e32 v91, v91, v185
	v_add_f32_dpp v95, v95, v95 row_half_mirror row_mask:0xf bank_mask:0xf bound_ctrl:1
	v_add_f32_dpp v94, v94, v94 row_half_mirror row_mask:0xf bank_mask:0xf bound_ctrl:1
	s_waitcnt lgkmcnt(0)
; #define LAS __attribute__((address_space(3)))
; template <int CTRL> __device__ __forceinline__ float dppf(float v) { return __int_as_float(__builtin_amdgcn_update_dpp(0, __float_as_int(v), CTRL, 0xf, 0xf, true)); }
; __device__ __forceinline__ void scan_phase(const Args& a, LAS unsigned char* lds, const bf16* Z, const float* W, const bf16* Aa, const bf16* KK, float* Y, int tid, int lane, int wave) {
;     ...
;                 for (int q = 0; q < SCH; ++q) {
;                     const f32x4 wv = pw[q % 3], kv = pk[q % 3], av = pa[q % 3], bv = pb[q % 3], rv = pr[q % 3]; const float vv = pv[q % 3];
;                     if (q + 2 < SCH) {
;                         const LAS float* p = sb + (q + 2) * SROW; const int i = (q + 2) % 3;
;                         pw[i] = *(const LAS f32x4*)p; pk[i] = *(const LAS f32x4*)(p + 64); pa[i] = *(const LAS f32x4*)(p + 128); pb[i] = *(const LAS f32x4*)(p + 192); pr[i] = *(const LAS f32x4*)(p + 256);
;                         pv[i] = vb[(q + 2) * SROW];
;                     }
;                     f32x2 t2 = S01 * (f32x2){av.x, av.y}; t2 = S23 * (f32x2){av.z, av.w} + t2;
;                     float sa = t2.x + t2.y;
;                     sa += dppf<0xB1>(sa); yd += dppf<0xB1>(yd);
;                     sa += dppf<0x4E>(sa); yd += dppf<0x4E>(yd);
;                     sa += dppf<0x141>(sa); yd += dppf<0x141>(yd);
;                     sa += dppf<0x140>(sa); yd += dppf<0x140>(yd);
;                     if (q > 0) { if (q <= 16) ykA = (j == q - 1) ? yd : ykA; else ykB = (j == q - 17) ? yd : ykB; }
;                     const f32x2 u01 = S01 * (f32x2){wv.x, wv.y} + (f32x2){kv.x, kv.y} * vv, u23 = S23 * (f32x2){wv.z, wv.w} + (f32x2){kv.z, kv.w} * vv;
;                     S01 = u01 + (f32x2){bv.x, bv.y} * sa; S23 = u23 + (f32x2){bv.z, bv.w} * sa;
;                     f32x2 y2 = S01 * (f32x2){rv.x, rv.y}; y2 = S23 * (f32x2){rv.z, rv.w} + y2;
;                     yd = y2.x + y2.y;
;                 }
	v_fma_f32 v86, v86, v182, v90
	v_fma_f32 v87, v87, v182, v91
	v_add_f32_dpp v95, v95, v95 row_mirror row_mask:0xf bank_mask:0xf bound_ctrl:1
	v_add_f32_dpp v94, v94, v94 row_mirror row_mask:0xf bank_mask:0xf bound_ctrl:1
	v_cndmask_b32_e64 v95, v196, v95, s[90:91]
	v_mul_f32_e32 v90, v92, v186
	v_mul_f32_e32 v91, v93, v187
	v_fma_f32 v82, v82, v94, v86
	v_fma_f32 v83, v83, v94, v87
	v_fma_f32 v88, v88, v182, v90
	v_fma_f32 v89, v89, v182, v91
	ds_read_b128 v[110:113], v195 offset:9408
	ds_read_b128 v[106:109], v195 offset:9664
	ds_read_b128 v[114:117], v195 offset:9920
	ds_read_b128 v[102:105], v195 offset:10176
	ds_read_b128 v[98:101], v195 offset:10432
	ds_read_b32 v188, v127 offset:10688
	v_fma_f32 v84, v84, v94, v88
	v_fma_f32 v85, v85, v94, v89
	v_mul_f32_e32 v78, v78, v82
	v_mul_f32_e32 v79, v79, v83
	ds_read_b128 v[58:61], v195 offset:10752
	ds_read_b128 v[62:65], v195 offset:11008
	ds_read_b128 v[66:69], v195 offset:11264
	ds_read_b128 v[70:73], v195 offset:11520
	ds_read_b128 v[74:77], v195 offset:11776
	ds_read_b32 v0, v127 offset:12032
	v_fmac_f32_e32 v78, v80, v84
	v_fmac_f32_e32 v79, v81, v85
	ds_read_b128 v[184:187], v195 offset:12096
	ds_read_b128 v[196:199], v195 offset:12352
	ds_read_b128 v[200:203], v195 offset:12608
	ds_read_b128 v[204:207], v195 offset:12864
	ds_read_b128 v[208:211], v195 offset:13120
	ds_read_b32 v182, v127 offset:13376
	v_add_f32_e32 v80, v78, v79
	s_waitcnt lgkmcnt(14)
	v_mul_f32_e32 v78, v114, v82
	v_mul_f32_e32 v79, v115, v83
	s_nop 0
	v_fmac_f32_e32 v78, v116, v84
	v_fmac_f32_e32 v79, v117, v85
	s_nop 0
	v_add_f32_e32 v78, v78, v79
	v_add_f32_dpp v79, v80, v80 quad_perm:[1,0,3,2] row_mask:0xf bank_mask:0xf bound_ctrl:1
	v_mul_f32_e32 v80, v110, v82
	v_mul_f32_e32 v81, v111, v83
	v_add_f32_dpp v78, v78, v78 quad_perm:[1,0,3,2] row_mask:0xf bank_mask:0xf bound_ctrl:1
	v_add_f32_dpp v79, v79, v79 quad_perm:[2,3,0,1] row_mask:0xf bank_mask:0xf bound_ctrl:1
	s_waitcnt lgkmcnt(12)
	v_fmac_f32_e32 v80, v106, v188
	v_fmac_f32_e32 v81, v107, v188
	v_add_f32_dpp v78, v78, v78 quad_perm:[2,3,0,1] row_mask:0xf bank_mask:0xf bound_ctrl:1
	v_add_f32_dpp v79, v79, v79 row_half_mirror row_mask:0xf bank_mask:0xf bound_ctrl:1
	v_mul_f32_e32 v82, v112, v84
	v_mul_f32_e32 v83, v113, v85
	v_add_f32_dpp v78, v78, v78 row_half_mirror row_mask:0xf bank_mask:0xf bound_ctrl:1
	v_add_f32_dpp v79, v79, v79 row_mirror row_mask:0xf bank_mask:0xf bound_ctrl:1
	v_fmac_f32_e32 v82, v108, v188
	v_fmac_f32_e32 v83, v109, v188
	v_add_f32_dpp v78, v78, v78 row_mirror row_mask:0xf bank_mask:0xf bound_ctrl:1
	v_fmac_f32_e32 v80, v102, v78
	v_fmac_f32_e32 v81, v103, v78
	v_cndmask_b32_e64 v86, v95, v79, s[60:61]
	v_fma_f32 v79, v105, v78, v83
	v_fma_f32 v78, v104, v78, v82
	v_mul_f32_e32 v82, v98, v80
	v_mul_f32_e32 v83, v99, v81
	s_waitcnt lgkmcnt(9)
	v_mul_f32_e32 v66, v66, v80
	v_mul_f32_e32 v67, v67, v81
	v_fmac_f32_e32 v82, v100, v78
	v_fmac_f32_e32 v83, v101, v79
	v_fmac_f32_e32 v66, v68, v78
	v_fmac_f32_e32 v67, v69, v79
	v_add_f32_e32 v82, v82, v83
	v_add_f32_e32 v66, v66, v67
	v_mul_f32_e32 v58, v58, v80
	v_mul_f32_e32 v59, v59, v81
	v_add_f32_dpp v67, v82, v82 quad_perm:[1,0,3,2] row_mask:0xf bank_mask:0xf bound_ctrl:1
	v_add_f32_dpp v66, v66, v66 quad_perm:[1,0,3,2] row_mask:0xf bank_mask:0xf bound_ctrl:1
	s_waitcnt lgkmcnt(6)
	v_fmac_f32_e32 v58, v62, v0
	v_fmac_f32_e32 v59, v63, v0
	v_add_f32_dpp v67, v67, v67 quad_perm:[2,3,0,1] row_mask:0xf bank_mask:0xf bound_ctrl:1
	v_add_f32_dpp v66, v66, v66 quad_perm:[2,3,0,1] row_mask:0xf bank_mask:0xf bound_ctrl:1
	v_mul_f32_e32 v60, v60, v78
	v_mul_f32_e32 v61, v61, v79
	v_add_f32_dpp v67, v67, v67 row_half_mirror row_mask:0xf bank_mask:0xf bound_ctrl:1
	v_add_f32_dpp v66, v66, v66 row_half_mirror row_mask:0xf bank_mask:0xf bound_ctrl:1
	v_fmac_f32_e32 v60, v64, v0
	v_fmac_f32_e32 v61, v65, v0
	v_add_f32_dpp v67, v67, v67 row_mirror row_mask:0xf bank_mask:0xf bound_ctrl:1
	v_add_f32_dpp v66, v66, v66 row_mirror row_mask:0xf bank_mask:0xf bound_ctrl:1
	v_cndmask_b32_e64 v67, v86, v67, s[62:63]
	v_fmac_f32_e32 v58, v70, v66
	v_fmac_f32_e32 v59, v71, v66
	v_fmac_f32_e32 v60, v72, v66
	v_fmac_f32_e32 v61, v73, v66
	v_mul_f32_e32 v62, v74, v58
	v_mul_f32_e32 v63, v75, v59
	ds_read_b128 v[212:215], v195 offset:13440
	ds_read_b128 v[218:221], v195 offset:13696
	ds_read_b128 v[222:225], v195 offset:13952
	ds_read_b128 v[226:229], v195 offset:14208
	ds_read_b128 v[230:233], v195 offset:14464
	ds_read_b32 v188, v127 offset:14720
	v_fmac_f32_e32 v62, v76, v60
	v_fmac_f32_e32 v63, v77, v61
	ds_read_b128 v[82:85], v195 offset:14784
	ds_read_b128 v[86:89], v195 offset:15040
	ds_read_b128 v[94:97], v195 offset:15296
	ds_read_b128 v[90:93], v195 offset:15552
	ds_read_b128 v[78:81], v195 offset:15808
	ds_read_b32 v234, v127 offset:16064
	v_add_f32_e32 v0, v62, v63
	s_waitcnt lgkmcnt(14)
	v_mul_f32_e32 v62, v200, v58
	v_mul_f32_e32 v63, v201, v59
	v_mul_f32_e32 v58, v184, v58
	v_mul_f32_e32 v59, v185, v59
	v_fmac_f32_e32 v62, v202, v60
	v_fmac_f32_e32 v63, v203, v61
	v_add_f32_dpp v0, v0, v0 quad_perm:[1,0,3,2] row_mask:0xf bank_mask:0xf bound_ctrl:1
	v_add_f32_e32 v62, v62, v63
	s_waitcnt lgkmcnt(12)
; #define LAS __attribute__((address_space(3)))
; template <int CTRL> __device__ __forceinline__ float dppf(float v) { return __int_as_float(__builtin_amdgcn_update_dpp(0, __float_as_int(v), CTRL, 0xf, 0xf, true)); }
; __device__ __forceinline__ void scan_phase(const Args& a, LAS unsigned char* lds, const bf16* Z, const float* W, const bf16* Aa, const bf16* KK, float* Y, int tid, int lane, int wave) {
;     ...
;                 for (int q = 0; q < SCH; ++q) {
;                     const f32x4 wv = pw[q % 3], kv = pk[q % 3], av = pa[q % 3], bv = pb[q % 3], rv = pr[q % 3]; const float vv = pv[q % 3];
;                     if (q + 2 < SCH) {
;                         const LAS float* p = sb + (q + 2) * SROW; const int i = (q + 2) % 3;
;                         pw[i] = *(const LAS f32x4*)p; pk[i] = *(const LAS f32x4*)(p + 64); pa[i] = *(const LAS f32x4*)(p + 128); pb[i] = *(const LAS f32x4*)(p + 192); pr[i] = *(const LAS f32x4*)(p + 256);
;                         pv[i] = vb[(q + 2) * SROW];
;                     }
;                     f32x2 t2 = S01 * (f32x2){av.x, av.y}; t2 = S23 * (f32x2){av.z, av.w} + t2;
;                     float sa = t2.x + t2.y;
;                     sa += dppf<0xB1>(sa); yd += dppf<0xB1>(yd);
;                     sa += dppf<0x4E>(sa); yd += dppf<0x4E>(yd);
;                     sa += dppf<0x141>(sa); yd += dppf<0x141>(yd);
;                     sa += dppf<0x140>(sa); yd += dppf<0x140>(yd);
;                     if (q > 0) { if (q <= 16) ykA = (j == q - 1) ? yd : ykA; else ykB = (j == q - 17) ? yd : ykB; }
;                     const f32x2 u01 = S01 * (f32x2){wv.x, wv.y} + (f32x2){kv.x, kv.y} * vv, u23 = S23 * (f32x2){wv.z, wv.w} + (f32x2){kv.z, kv.w} * vv;
;                     S01 = u01 + (f32x2){bv.x, bv.y} * sa; S23 = u23 + (f32x2){bv.z, bv.w} * sa;
;                     f32x2 y2 = S01 * (f32x2){rv.x, rv.y}; y2 = S23 * (f32x2){rv.z, rv.w} + y2;
;                     yd = y2.x + y2.y;
;                 }
	v_fmac_f32_e32 v58, v196, v182
	v_fmac_f32_e32 v59, v197, v182
	v_add_f32_dpp v0, v0, v0 quad_perm:[2,3,0,1] row_mask:0xf bank_mask:0xf bound_ctrl:1
	v_add_f32_dpp v62, v62, v62 quad_perm:[1,0,3,2] row_mask:0xf bank_mask:0xf bound_ctrl:1
	v_mul_f32_e32 v60, v186, v60
	v_mul_f32_e32 v61, v187, v61
	v_add_f32_dpp v63, v0, v0 row_half_mirror row_mask:0xf bank_mask:0xf bound_ctrl:1
	v_add_f32_dpp v62, v62, v62 quad_perm:[2,3,0,1] row_mask:0xf bank_mask:0xf bound_ctrl:1
	v_fmac_f32_e32 v60, v198, v182
	v_fmac_f32_e32 v61, v199, v182
	ds_read_b128 v[102:105], v195 offset:16128
	ds_read_b128 v[106:109], v195 offset:16384
	ds_read_b128 v[114:117], v195 offset:16640
	ds_read_b128 v[110:113], v195 offset:16896
	ds_read_b128 v[98:101], v195 offset:17152
	ds_read_b32 v184, v127 offset:17408
	v_add_f32_dpp v62, v62, v62 row_half_mirror row_mask:0xf bank_mask:0xf bound_ctrl:1
	s_nop 1
	v_add_f32_dpp v0, v62, v62 row_mirror row_mask:0xf bank_mask:0xf bound_ctrl:1
	v_add_f32_dpp v62, v63, v63 row_mirror row_mask:0xf bank_mask:0xf bound_ctrl:1
	v_fmac_f32_e32 v58, v204, v0
	v_fmac_f32_e32 v59, v205, v0
	v_cndmask_b32_e64 v64, v67, v62, s[64:65]
	v_fmac_f32_e32 v60, v206, v0
	v_fmac_f32_e32 v61, v207, v0
	v_mul_f32_e32 v62, v208, v58
	v_mul_f32_e32 v63, v209, v59
	s_nop 0
	v_fmac_f32_e32 v62, v210, v60
	v_fmac_f32_e32 v63, v211, v61
	s_nop 0
	v_add_f32_e32 v0, v62, v63
	s_waitcnt lgkmcnt(14)
	v_mul_f32_e32 v62, v222, v58
	v_mul_f32_e32 v63, v223, v59
	v_mul_f32_e32 v58, v212, v58
	v_mul_f32_e32 v59, v213, v59
	v_fmac_f32_e32 v62, v224, v60
	v_fmac_f32_e32 v63, v225, v61
	v_add_f32_dpp v0, v0, v0 quad_perm:[1,0,3,2] row_mask:0xf bank_mask:0xf bound_ctrl:1
	v_add_f32_e32 v62, v62, v63
	s_waitcnt lgkmcnt(12)
	v_fmac_f32_e32 v58, v218, v188
	v_fmac_f32_e32 v59, v219, v188
	v_add_f32_dpp v0, v0, v0 quad_perm:[2,3,0,1] row_mask:0xf bank_mask:0xf bound_ctrl:1
	v_add_f32_dpp v62, v62, v62 quad_perm:[1,0,3,2] row_mask:0xf bank_mask:0xf bound_ctrl:1
	v_mul_f32_e32 v60, v214, v60
	v_mul_f32_e32 v61, v215, v61
	v_add_f32_dpp v63, v0, v0 row_half_mirror row_mask:0xf bank_mask:0xf bound_ctrl:1
	v_add_f32_dpp v62, v62, v62 quad_perm:[2,3,0,1] row_mask:0xf bank_mask:0xf bound_ctrl:1
	v_fmac_f32_e32 v60, v220, v188
	v_fmac_f32_e32 v61, v221, v188
	s_nop 0
	v_add_f32_dpp v62, v62, v62 row_half_mirror row_mask:0xf bank_mask:0xf bound_ctrl:1
	s_nop 1
	v_add_f32_dpp v0, v62, v62 row_mirror row_mask:0xf bank_mask:0xf bound_ctrl:1
	v_fma_f32 v186, v226, v0, v58
	v_fma_f32 v187, v227, v0, v59
	v_fma_f32 v196, v228, v0, v60
	v_fma_f32 v197, v229, v0, v61
	v_mul_f32_e32 v58, v230, v186
	v_mul_f32_e32 v59, v231, v187
	s_waitcnt lgkmcnt(9)
	v_mul_f32_e32 v94, v94, v186
	v_mul_f32_e32 v95, v95, v187
	v_fmac_f32_e32 v58, v232, v196
	v_fmac_f32_e32 v59, v233, v197
	v_fmac_f32_e32 v94, v96, v196
	v_fmac_f32_e32 v95, v97, v197
	v_add_f32_e32 v185, v58, v59
	v_add_f32_e32 v94, v94, v95
	v_mul_f32_e32 v82, v82, v186
	v_mul_f32_e32 v83, v83, v187
	v_add_f32_dpp v95, v185, v185 quad_perm:[1,0,3,2] row_mask:0xf bank_mask:0xf bound_ctrl:1
	v_add_f32_dpp v94, v94, v94 quad_perm:[1,0,3,2] row_mask:0xf bank_mask:0xf bound_ctrl:1
	s_waitcnt lgkmcnt(6)
	v_fmac_f32_e32 v82, v86, v234
	v_fmac_f32_e32 v83, v87, v234
	v_add_f32_dpp v95, v95, v95 quad_perm:[2,3,0,1] row_mask:0xf bank_mask:0xf bound_ctrl:1
	v_add_f32_dpp v94, v94, v94 quad_perm:[2,3,0,1] row_mask:0xf bank_mask:0xf bound_ctrl:1
	v_mul_f32_e32 v84, v84, v196
	v_mul_f32_e32 v85, v85, v197
	v_add_f32_dpp v95, v95, v95 row_half_mirror row_mask:0xf bank_mask:0xf bound_ctrl:1
	v_add_f32_dpp v94, v94, v94 row_half_mirror row_mask:0xf bank_mask:0xf bound_ctrl:1
	v_fmac_f32_e32 v84, v88, v234
	v_fmac_f32_e32 v85, v89, v234
	v_add_f32_dpp v95, v95, v95 row_mirror row_mask:0xf bank_mask:0xf bound_ctrl:1
	v_add_f32_dpp v94, v94, v94 row_mirror row_mask:0xf bank_mask:0xf bound_ctrl:1
	v_fma_f32 v186, v90, v94, v82
	v_fma_f32 v187, v91, v94, v83
	v_fma_f32 v196, v92, v94, v84
	v_fma_f32 v197, v93, v94, v85
	v_mul_f32_e32 v78, v78, v186
	v_mul_f32_e32 v79, v79, v187
	s_waitcnt lgkmcnt(3)
	v_mul_f32_e32 v114, v114, v186
	v_mul_f32_e32 v115, v115, v187
	v_fmac_f32_e32 v78, v80, v196
	v_fmac_f32_e32 v79, v81, v197
	v_fmac_f32_e32 v114, v116, v196
	v_fmac_f32_e32 v115, v117, v197
	v_add_f32_e32 v188, v78, v79
	v_add_f32_e32 v114, v114, v115
	v_add_f32_dpp v62, v63, v63 row_mirror row_mask:0xf bank_mask:0xf bound_ctrl:1
	v_add_f32_dpp v115, v188, v188 quad_perm:[1,0,3,2] row_mask:0xf bank_mask:0xf bound_ctrl:1
	v_add_f32_dpp v114, v114, v114 quad_perm:[1,0,3,2] row_mask:0xf bank_mask:0xf bound_ctrl:1
	v_cndmask_b32_e64 v182, v64, v62, s[66:67]
	v_add_f32_dpp v115, v115, v115 quad_perm:[2,3,0,1] row_mask:0xf bank_mask:0xf bound_ctrl:1
	v_add_f32_dpp v114, v114, v114 quad_perm:[2,3,0,1] row_mask:0xf bank_mask:0xf bound_ctrl:1
	v_cndmask_b32_e64 v185, v182, v95, s[68:69]
	v_add_f32_dpp v115, v115, v115 row_half_mirror row_mask:0xf bank_mask:0xf bound_ctrl:1
	v_add_f32_dpp v114, v114, v114 row_half_mirror row_mask:0xf bank_mask:0xf bound_ctrl:1
	v_mul_f32_e32 v102, v102, v186
	v_mul_f32_e32 v103, v103, v187
	ds_read_b128 v[70:73], v195 offset:17472
	ds_read_b128 v[66:69], v195 offset:17728
	ds_read_b128 v[74:77], v195 offset:17984
	ds_read_b128 v[62:65], v195 offset:18240
	ds_read_b128 v[58:61], v195 offset:18496
	ds_read_b32 v0, v127 offset:18752
	v_add_f32_dpp v114, v114, v114 row_mirror row_mask:0xf bank_mask:0xf bound_ctrl:1
	v_add_f32_dpp v115, v115, v115 row_mirror row_mask:0xf bank_mask:0xf bound_ctrl:1
	s_waitcnt lgkmcnt(6)
; #define LAS __attribute__((address_space(3)))
; template <int CTRL> __device__ __forceinline__ float dppf(float v) { return __int_as_float(__builtin_amdgcn_update_dpp(0, __float_as_int(v), CTRL, 0xf, 0xf, true)); }
; __device__ __forceinline__ void scan_phase(const Args& a, LAS unsigned char* lds, const bf16* Z, const float* W, const bf16* Aa, const bf16* KK, float* Y, int tid, int lane, int wave) {
;     ...
;                 for (int q = 0; q < SCH; ++q) {
;                     const f32x4 wv = pw[q % 3], kv = pk[q % 3], av = pa[q % 3], bv = pb[q % 3], rv = pr[q % 3]; const float vv = pv[q % 3];
;                     if (q + 2 < SCH) {
;                         const LAS float* p = sb + (q + 2) * SROW; const int i = (q + 2) % 3;
;                         pw[i] = *(const LAS f32x4*)p; pk[i] = *(const LAS f32x4*)(p + 64); pa[i] = *(const LAS f32x4*)(p + 128); pb[i] = *(const LAS f32x4*)(p + 192); pr[i] = *(const LAS f32x4*)(p + 256);
;                         pv[i] = vb[(q + 2) * SROW];
;                     }
;                     f32x2 t2 = S01 * (f32x2){av.x, av.y}; t2 = S23 * (f32x2){av.z, av.w} + t2;
;                     float sa = t2.x + t2.y;
;                     sa += dppf<0xB1>(sa); yd += dppf<0xB1>(yd);
;                     sa += dppf<0x4E>(sa); yd += dppf<0x4E>(yd);
;                     sa += dppf<0x141>(sa); yd += dppf<0x141>(yd);
;                     sa += dppf<0x140>(sa); yd += dppf<0x140>(yd);
;                     if (q > 0) { if (q <= 16) ykA = (j == q - 1) ? yd : ykA; else ykB = (j == q - 17) ? yd : ykB; }
;                     const f32x2 u01 = S01 * (f32x2){wv.x, wv.y} + (f32x2){kv.x, kv.y} * vv, u23 = S23 * (f32x2){wv.z, wv.w} + (f32x2){kv.z, kv.w} * vv;
;                     S01 = u01 + (f32x2){bv.x, bv.y} * sa; S23 = u23 + (f32x2){bv.z, bv.w} * sa;
;                     f32x2 y2 = S01 * (f32x2){rv.x, rv.y}; y2 = S23 * (f32x2){rv.z, rv.w} + y2;
;                     yd = y2.x + y2.y;
;                 }
	v_fmac_f32_e32 v102, v106, v184
	v_fmac_f32_e32 v103, v107, v184
	v_mul_f32_e32 v104, v104, v196
	v_mul_f32_e32 v105, v105, v197
	v_fma_f32 v186, v110, v114, v102
	v_fma_f32 v187, v111, v114, v103
	v_fmac_f32_e32 v104, v108, v184
	v_fmac_f32_e32 v105, v109, v184
	v_cndmask_b32_e64 v198, v185, v115, s[70:71]
	v_fma_f32 v184, v112, v114, v104
	v_fma_f32 v185, v113, v114, v105
	v_mul_f32_e32 v98, v98, v186
	v_mul_f32_e32 v99, v99, v187
	s_waitcnt lgkmcnt(3)
	v_mul_f32_e32 v74, v74, v186
	v_mul_f32_e32 v75, v75, v187
	v_fmac_f32_e32 v98, v100, v184
	v_fmac_f32_e32 v99, v101, v185
	v_fmac_f32_e32 v74, v76, v184
	v_fmac_f32_e32 v75, v77, v185
	v_add_f32_e32 v196, v98, v99
	v_add_f32_e32 v74, v74, v75
	v_mul_f32_e32 v70, v70, v186
	v_mul_f32_e32 v71, v71, v187
	v_add_f32_dpp v75, v196, v196 quad_perm:[1,0,3,2] row_mask:0xf bank_mask:0xf bound_ctrl:1
	v_add_f32_dpp v74, v74, v74 quad_perm:[1,0,3,2] row_mask:0xf bank_mask:0xf bound_ctrl:1
	s_waitcnt lgkmcnt(0)
	v_fma_f32 v66, v66, v0, v70
	v_fma_f32 v67, v67, v0, v71
	v_add_f32_dpp v75, v75, v75 quad_perm:[2,3,0,1] row_mask:0xf bank_mask:0xf bound_ctrl:1
	v_add_f32_dpp v74, v74, v74 quad_perm:[2,3,0,1] row_mask:0xf bank_mask:0xf bound_ctrl:1
	v_mul_f32_e32 v70, v72, v184
	v_mul_f32_e32 v71, v73, v185
	v_add_f32_dpp v75, v75, v75 row_half_mirror row_mask:0xf bank_mask:0xf bound_ctrl:1
	v_add_f32_dpp v74, v74, v74 row_half_mirror row_mask:0xf bank_mask:0xf bound_ctrl:1
	ds_read_b128 v[90:93], v195 offset:18816
	ds_read_b128 v[86:89], v195 offset:19072
	ds_read_b128 v[94:97], v195 offset:19328
	ds_read_b128 v[82:85], v195 offset:19584
	ds_read_b128 v[78:81], v195 offset:19840
	ds_read_b32 v182, v127 offset:20096
	v_add_f32_dpp v74, v74, v74 row_mirror row_mask:0xf bank_mask:0xf bound_ctrl:1
	v_add_f32_dpp v75, v75, v75 row_mirror row_mask:0xf bank_mask:0xf bound_ctrl:1
	v_fma_f32 v68, v68, v0, v70
	v_fma_f32 v69, v69, v0, v71
	v_fma_f32 v184, v62, v74, v66
	v_fma_f32 v185, v63, v74, v67
	v_fma_f32 v186, v64, v74, v68
	v_fma_f32 v187, v65, v74, v69
	v_mul_f32_e32 v58, v58, v184
	v_mul_f32_e32 v59, v59, v185
	s_waitcnt lgkmcnt(3)
	v_mul_f32_e32 v94, v94, v184
	v_mul_f32_e32 v95, v95, v185
	v_fmac_f32_e32 v58, v60, v186
	v_fmac_f32_e32 v59, v61, v187
	v_fmac_f32_e32 v94, v96, v186
	v_fmac_f32_e32 v95, v97, v187
	v_add_f32_e32 v197, v58, v59
	v_add_f32_e32 v94, v94, v95
	v_cndmask_b32_e64 v196, v198, v75, s[72:73]
	v_add_f32_dpp v95, v197, v197 quad_perm:[1,0,3,2] row_mask:0xf bank_mask:0xf bound_ctrl:1
	v_add_f32_dpp v94, v94, v94 quad_perm:[1,0,3,2] row_mask:0xf bank_mask:0xf bound_ctrl:1
	v_mul_f32_e32 v90, v90, v184
	v_mul_f32_e32 v91, v91, v185
	v_add_f32_dpp v95, v95, v95 quad_perm:[2,3,0,1] row_mask:0xf bank_mask:0xf bound_ctrl:1
	v_add_f32_dpp v94, v94, v94 quad_perm:[2,3,0,1] row_mask:0xf bank_mask:0xf bound_ctrl:1
	s_waitcnt lgkmcnt(0)
	v_fma_f32 v86, v86, v182, v90
	v_fma_f32 v87, v87, v182, v91
	v_add_f32_dpp v95, v95, v95 row_half_mirror row_mask:0xf bank_mask:0xf bound_ctrl:1
	v_add_f32_dpp v94, v94, v94 row_half_mirror row_mask:0xf bank_mask:0xf bound_ctrl:1
	v_mul_f32_e32 v90, v92, v186
	v_mul_f32_e32 v91, v93, v187
	v_add_f32_dpp v95, v95, v95 row_mirror row_mask:0xf bank_mask:0xf bound_ctrl:1
	v_add_f32_dpp v94, v94, v94 row_mirror row_mask:0xf bank_mask:0xf bound_ctrl:1
	v_cndmask_b32_e64 v95, v196, v95, s[74:75]
	v_fma_f32 v88, v88, v182, v90
	v_fma_f32 v89, v89, v182, v91
	v_fma_f32 v82, v82, v94, v86
	v_fma_f32 v83, v83, v94, v87
	ds_read_b128 v[110:113], v195 offset:20160
	ds_read_b128 v[106:109], v195 offset:20416
	ds_read_b128 v[114:117], v195 offset:20672
	ds_read_b128 v[102:105], v195 offset:20928
	ds_read_b128 v[98:101], v195 offset:21184
	ds_read_b32 v188, v127 offset:21440
	v_fma_f32 v84, v84, v94, v88
	v_fma_f32 v85, v85, v94, v89
	v_mul_f32_e32 v78, v78, v82
	v_mul_f32_e32 v79, v79, v83
	ds_read_b128 v[58:61], v195 offset:21504
	ds_read_b128 v[62:65], v195 offset:21760
	ds_read_b128 v[66:69], v195 offset:22016
	ds_read_b128 v[70:73], v195 offset:22272
	ds_read_b128 v[74:77], v195 offset:22528
	ds_read_b32 v0, v127 offset:22784
	v_fmac_f32_e32 v78, v80, v84
	v_fmac_f32_e32 v79, v81, v85
	ds_read_b128 v[184:187], v195 offset:22848
	ds_read_b128 v[198:201], v195 offset:23104
	ds_read_b128 v[202:205], v195 offset:23360
	ds_read_b128 v[206:209], v195 offset:23616
	ds_read_b128 v[210:213], v195 offset:23872
	ds_read_b32 v182, v127 offset:24128
	v_add_f32_e32 v80, v78, v79
	s_waitcnt lgkmcnt(14)
	v_mul_f32_e32 v78, v114, v82
	v_mul_f32_e32 v79, v115, v83
	s_nop 0
	v_fmac_f32_e32 v78, v116, v84
	v_fmac_f32_e32 v79, v117, v85
	s_nop 0
	v_add_f32_e32 v78, v78, v79
	v_add_f32_dpp v79, v80, v80 quad_perm:[1,0,3,2] row_mask:0xf bank_mask:0xf bound_ctrl:1
	v_mul_f32_e32 v80, v110, v82
	v_mul_f32_e32 v81, v111, v83
	v_add_f32_dpp v78, v78, v78 quad_perm:[1,0,3,2] row_mask:0xf bank_mask:0xf bound_ctrl:1
	v_add_f32_dpp v79, v79, v79 quad_perm:[2,3,0,1] row_mask:0xf bank_mask:0xf bound_ctrl:1
	s_waitcnt lgkmcnt(12)
	v_fmac_f32_e32 v80, v106, v188
	v_fmac_f32_e32 v81, v107, v188
	v_add_f32_dpp v78, v78, v78 quad_perm:[2,3,0,1] row_mask:0xf bank_mask:0xf bound_ctrl:1
	v_add_f32_dpp v79, v79, v79 row_half_mirror row_mask:0xf bank_mask:0xf bound_ctrl:1
	v_mul_f32_e32 v82, v112, v84
	v_mul_f32_e32 v83, v113, v85
	v_add_f32_dpp v78, v78, v78 row_half_mirror row_mask:0xf bank_mask:0xf bound_ctrl:1
	v_add_f32_dpp v79, v79, v79 row_mirror row_mask:0xf bank_mask:0xf bound_ctrl:1
	v_fmac_f32_e32 v82, v108, v188
	v_fmac_f32_e32 v83, v109, v188
	v_add_f32_dpp v78, v78, v78 row_mirror row_mask:0xf bank_mask:0xf bound_ctrl:1
	v_fmac_f32_e32 v80, v102, v78
	v_fmac_f32_e32 v81, v103, v78
	v_cndmask_b32_e64 v86, v95, v79, s[76:77]
	v_fma_f32 v79, v105, v78, v83
	v_fma_f32 v78, v104, v78, v82
	v_mul_f32_e32 v82, v98, v80
	v_mul_f32_e32 v83, v99, v81
	s_waitcnt lgkmcnt(9)
; #define LAS __attribute__((address_space(3)))
; template <int CTRL> __device__ __forceinline__ float dppf(float v) { return __int_as_float(__builtin_amdgcn_update_dpp(0, __float_as_int(v), CTRL, 0xf, 0xf, true)); }
; __device__ __forceinline__ void scan_phase(const Args& a, LAS unsigned char* lds, const bf16* Z, const float* W, const bf16* Aa, const bf16* KK, float* Y, int tid, int lane, int wave) {
;     ...
;                 for (int q = 0; q < SCH; ++q) {
;                     const f32x4 wv = pw[q % 3], kv = pk[q % 3], av = pa[q % 3], bv = pb[q % 3], rv = pr[q % 3]; const float vv = pv[q % 3];
;                     if (q + 2 < SCH) {
;                         const LAS float* p = sb + (q + 2) * SROW; const int i = (q + 2) % 3;
;                         pw[i] = *(const LAS f32x4*)p; pk[i] = *(const LAS f32x4*)(p + 64); pa[i] = *(const LAS f32x4*)(p + 128); pb[i] = *(const LAS f32x4*)(p + 192); pr[i] = *(const LAS f32x4*)(p + 256);
;                         pv[i] = vb[(q + 2) * SROW];
;                     }
;                     f32x2 t2 = S01 * (f32x2){av.x, av.y}; t2 = S23 * (f32x2){av.z, av.w} + t2;
;                     float sa = t2.x + t2.y;
;                     sa += dppf<0xB1>(sa); yd += dppf<0xB1>(yd);
;                     sa += dppf<0x4E>(sa); yd += dppf<0x4E>(yd);
;                     sa += dppf<0x141>(sa); yd += dppf<0x141>(yd);
;                     sa += dppf<0x140>(sa); yd += dppf<0x140>(yd);
;                     if (q > 0) { if (q <= 16) ykA = (j == q - 1) ? yd : ykA; else ykB = (j == q - 17) ? yd : ykB; }
;                     const f32x2 u01 = S01 * (f32x2){wv.x, wv.y} + (f32x2){kv.x, kv.y} * vv, u23 = S23 * (f32x2){wv.z, wv.w} + (f32x2){kv.z, kv.w} * vv;
;                     S01 = u01 + (f32x2){bv.x, bv.y} * sa; S23 = u23 + (f32x2){bv.z, bv.w} * sa;
;                     f32x2 y2 = S01 * (f32x2){rv.x, rv.y}; y2 = S23 * (f32x2){rv.z, rv.w} + y2;
;                     yd = y2.x + y2.y;
;                 }
	v_mul_f32_e32 v66, v66, v80
	v_mul_f32_e32 v67, v67, v81
	v_fmac_f32_e32 v82, v100, v78
	v_fmac_f32_e32 v83, v101, v79
	v_fmac_f32_e32 v66, v68, v78
	v_fmac_f32_e32 v67, v69, v79
	v_add_f32_e32 v82, v82, v83
	v_add_f32_e32 v66, v66, v67
	v_mul_f32_e32 v58, v58, v80
	v_mul_f32_e32 v59, v59, v81
	v_add_f32_dpp v67, v82, v82 quad_perm:[1,0,3,2] row_mask:0xf bank_mask:0xf bound_ctrl:1
	v_add_f32_dpp v66, v66, v66 quad_perm:[1,0,3,2] row_mask:0xf bank_mask:0xf bound_ctrl:1
	s_waitcnt lgkmcnt(6)
	v_fmac_f32_e32 v58, v62, v0
	v_fmac_f32_e32 v59, v63, v0
	v_add_f32_dpp v67, v67, v67 quad_perm:[2,3,0,1] row_mask:0xf bank_mask:0xf bound_ctrl:1
	v_add_f32_dpp v66, v66, v66 quad_perm:[2,3,0,1] row_mask:0xf bank_mask:0xf bound_ctrl:1
	v_mul_f32_e32 v60, v60, v78
	v_mul_f32_e32 v61, v61, v79
	v_add_f32_dpp v67, v67, v67 row_half_mirror row_mask:0xf bank_mask:0xf bound_ctrl:1
	v_add_f32_dpp v66, v66, v66 row_half_mirror row_mask:0xf bank_mask:0xf bound_ctrl:1
	v_fmac_f32_e32 v60, v64, v0
	v_fmac_f32_e32 v61, v65, v0
	v_add_f32_dpp v67, v67, v67 row_mirror row_mask:0xf bank_mask:0xf bound_ctrl:1
	v_add_f32_dpp v66, v66, v66 row_mirror row_mask:0xf bank_mask:0xf bound_ctrl:1
	v_fmac_f32_e32 v58, v70, v66
	v_fmac_f32_e32 v59, v71, v66
	v_fmac_f32_e32 v60, v72, v66
	v_fmac_f32_e32 v61, v73, v66
	v_mul_f32_e32 v62, v74, v58
	v_mul_f32_e32 v63, v75, v59
	ds_read_b128 v[218:221], v195 offset:24192
	ds_read_b128 v[222:225], v195 offset:24448
	ds_read_b128 v[226:229], v195 offset:24704
	ds_read_b128 v[230:233], v195 offset:24960
	ds_read_b128 v[234:237], v195 offset:25216
	ds_read_b32 v188, v127 offset:25472
	v_fmac_f32_e32 v62, v76, v60
	v_fmac_f32_e32 v63, v77, v61
	v_cndmask_b32_e64 v196, v86, v67, s[96:97]
	v_add_f32_e32 v0, v62, v63
	s_waitcnt lgkmcnt(9)
	v_mul_f32_e32 v62, v202, v58
	v_mul_f32_e32 v63, v203, v59
	v_mul_f32_e32 v58, v184, v58
	v_mul_f32_e32 v59, v185, v59
	v_fmac_f32_e32 v62, v204, v60
	v_fmac_f32_e32 v63, v205, v61
	v_add_f32_dpp v0, v0, v0 quad_perm:[1,0,3,2] row_mask:0xf bank_mask:0xf bound_ctrl:1
	v_add_f32_e32 v62, v62, v63
	s_waitcnt lgkmcnt(6)
	v_fmac_f32_e32 v58, v198, v182
	v_fmac_f32_e32 v59, v199, v182
	v_add_f32_dpp v0, v0, v0 quad_perm:[2,3,0,1] row_mask:0xf bank_mask:0xf bound_ctrl:1
	v_add_f32_dpp v62, v62, v62 quad_perm:[1,0,3,2] row_mask:0xf bank_mask:0xf bound_ctrl:1
	v_mul_f32_e32 v60, v186, v60
	v_mul_f32_e32 v61, v187, v61
	v_add_f32_dpp v63, v0, v0 row_half_mirror row_mask:0xf bank_mask:0xf bound_ctrl:1
	v_add_f32_dpp v62, v62, v62 quad_perm:[2,3,0,1] row_mask:0xf bank_mask:0xf bound_ctrl:1
	v_fmac_f32_e32 v60, v200, v182
	v_fmac_f32_e32 v61, v201, v182
	ds_read_b128 v[82:85], v195 offset:25536
	ds_read_b128 v[86:89], v195 offset:25792
	ds_read_b128 v[94:97], v195 offset:26048
	ds_read_b128 v[90:93], v195 offset:26304
	ds_read_b128 v[78:81], v195 offset:26560
	ds_read_b32 v214, v127 offset:26816
	v_add_f32_dpp v62, v62, v62 row_half_mirror row_mask:0xf bank_mask:0xf bound_ctrl:1
	ds_read_b128 v[102:105], v195 offset:26880
	ds_read_b128 v[106:109], v195 offset:27136
	ds_read_b128 v[114:117], v195 offset:27392
	ds_read_b128 v[110:113], v195 offset:27648
	ds_read_b128 v[98:101], v195 offset:27904
	ds_read_b32 v184, v127 offset:28160
	v_add_f32_dpp v0, v62, v62 row_mirror row_mask:0xf bank_mask:0xf bound_ctrl:1
	v_add_f32_dpp v62, v63, v63 row_mirror row_mask:0xf bank_mask:0xf bound_ctrl:1
	v_fmac_f32_e32 v58, v206, v0
	v_fmac_f32_e32 v59, v207, v0
	v_cndmask_b32_e64 v64, 0, v62, s[82:83]
	v_fmac_f32_e32 v60, v208, v0
	v_fmac_f32_e32 v61, v209, v0
	v_mul_f32_e32 v62, v210, v58
	v_mul_f32_e32 v63, v211, v59
	s_nop 0
	v_fmac_f32_e32 v62, v212, v60
	v_fmac_f32_e32 v63, v213, v61
	s_nop 0
	v_add_f32_e32 v0, v62, v63
	s_waitcnt lgkmcnt(14)
	v_mul_f32_e32 v62, v226, v58
	v_mul_f32_e32 v63, v227, v59
	v_mul_f32_e32 v58, v218, v58
	v_mul_f32_e32 v59, v219, v59
	v_fmac_f32_e32 v62, v228, v60
	v_fmac_f32_e32 v63, v229, v61
	v_add_f32_dpp v0, v0, v0 quad_perm:[1,0,3,2] row_mask:0xf bank_mask:0xf bound_ctrl:1
	v_add_f32_e32 v62, v62, v63
	s_waitcnt lgkmcnt(12)
	v_fmac_f32_e32 v58, v222, v188
	v_fmac_f32_e32 v59, v223, v188
	v_add_f32_dpp v0, v0, v0 quad_perm:[2,3,0,1] row_mask:0xf bank_mask:0xf bound_ctrl:1
	v_add_f32_dpp v62, v62, v62 quad_perm:[1,0,3,2] row_mask:0xf bank_mask:0xf bound_ctrl:1
	v_mul_f32_e32 v60, v220, v60
	v_mul_f32_e32 v61, v221, v61
	v_add_f32_dpp v63, v0, v0 row_half_mirror row_mask:0xf bank_mask:0xf bound_ctrl:1
	v_add_f32_dpp v62, v62, v62 quad_perm:[2,3,0,1] row_mask:0xf bank_mask:0xf bound_ctrl:1
	v_fmac_f32_e32 v60, v224, v188
	v_fmac_f32_e32 v61, v225, v188
	s_nop 0
	v_add_f32_dpp v62, v62, v62 row_half_mirror row_mask:0xf bank_mask:0xf bound_ctrl:1
	s_nop 1
	v_add_f32_dpp v0, v62, v62 row_mirror row_mask:0xf bank_mask:0xf bound_ctrl:1
	v_fma_f32 v186, v230, v0, v58
	v_fma_f32 v187, v231, v0, v59
	v_fma_f32 v198, v232, v0, v60
	v_fma_f32 v199, v233, v0, v61
	v_mul_f32_e32 v58, v234, v186
	v_mul_f32_e32 v59, v235, v187
	s_waitcnt lgkmcnt(9)
	v_mul_f32_e32 v94, v94, v186
	v_mul_f32_e32 v95, v95, v187
	v_fmac_f32_e32 v58, v236, v198
	v_fmac_f32_e32 v59, v237, v199
	v_fmac_f32_e32 v94, v96, v198
	v_fmac_f32_e32 v95, v97, v199
	v_add_f32_e32 v185, v58, v59
	v_add_f32_e32 v94, v94, v95
	v_mul_f32_e32 v82, v82, v186
	v_mul_f32_e32 v83, v83, v187
	v_add_f32_dpp v95, v185, v185 quad_perm:[1,0,3,2] row_mask:0xf bank_mask:0xf bound_ctrl:1
	v_add_f32_dpp v94, v94, v94 quad_perm:[1,0,3,2] row_mask:0xf bank_mask:0xf bound_ctrl:1
	s_waitcnt lgkmcnt(6)
; #define LAS __attribute__((address_space(3)))
; template <int CTRL> __device__ __forceinline__ float dppf(float v) { return __int_as_float(__builtin_amdgcn_update_dpp(0, __float_as_int(v), CTRL, 0xf, 0xf, true)); }
; __device__ __forceinline__ void scan_phase(const Args& a, LAS unsigned char* lds, const bf16* Z, const float* W, const bf16* Aa, const bf16* KK, float* Y, int tid, int lane, int wave) {
;     ...
;                 for (int q = 0; q < SCH; ++q) {
;                     const f32x4 wv = pw[q % 3], kv = pk[q % 3], av = pa[q % 3], bv = pb[q % 3], rv = pr[q % 3]; const float vv = pv[q % 3];
;                     if (q + 2 < SCH) {
;                         const LAS float* p = sb + (q + 2) * SROW; const int i = (q + 2) % 3;
;                         pw[i] = *(const LAS f32x4*)p; pk[i] = *(const LAS f32x4*)(p + 64); pa[i] = *(const LAS f32x4*)(p + 128); pb[i] = *(const LAS f32x4*)(p + 192); pr[i] = *(const LAS f32x4*)(p + 256);
;                         pv[i] = vb[(q + 2) * SROW];
;                     }
;                     f32x2 t2 = S01 * (f32x2){av.x, av.y}; t2 = S23 * (f32x2){av.z, av.w} + t2;
;                     float sa = t2.x + t2.y;
;                     sa += dppf<0xB1>(sa); yd += dppf<0xB1>(yd);
;                     sa += dppf<0x4E>(sa); yd += dppf<0x4E>(yd);
;                     sa += dppf<0x141>(sa); yd += dppf<0x141>(yd);
;                     sa += dppf<0x140>(sa); yd += dppf<0x140>(yd);
;                     if (q > 0) { if (q <= 16) ykA = (j == q - 1) ? yd : ykA; else ykB = (j == q - 17) ? yd : ykB; }
;                     const f32x2 u01 = S01 * (f32x2){wv.x, wv.y} + (f32x2){kv.x, kv.y} * vv, u23 = S23 * (f32x2){wv.z, wv.w} + (f32x2){kv.z, kv.w} * vv;
;                     S01 = u01 + (f32x2){bv.x, bv.y} * sa; S23 = u23 + (f32x2){bv.z, bv.w} * sa;
;                     f32x2 y2 = S01 * (f32x2){rv.x, rv.y}; y2 = S23 * (f32x2){rv.z, rv.w} + y2;
;                     yd = y2.x + y2.y;
;                 }
	v_fmac_f32_e32 v82, v86, v214
	v_fmac_f32_e32 v83, v87, v214
	v_add_f32_dpp v95, v95, v95 quad_perm:[2,3,0,1] row_mask:0xf bank_mask:0xf bound_ctrl:1
	v_add_f32_dpp v94, v94, v94 quad_perm:[2,3,0,1] row_mask:0xf bank_mask:0xf bound_ctrl:1
	v_mul_f32_e32 v84, v84, v198
	v_mul_f32_e32 v85, v85, v199
	v_add_f32_dpp v95, v95, v95 row_half_mirror row_mask:0xf bank_mask:0xf bound_ctrl:1
	v_add_f32_dpp v94, v94, v94 row_half_mirror row_mask:0xf bank_mask:0xf bound_ctrl:1
	v_fmac_f32_e32 v84, v88, v214
	v_fmac_f32_e32 v85, v89, v214
	v_add_f32_dpp v95, v95, v95 row_mirror row_mask:0xf bank_mask:0xf bound_ctrl:1
	v_add_f32_dpp v94, v94, v94 row_mirror row_mask:0xf bank_mask:0xf bound_ctrl:1
	v_fma_f32 v186, v90, v94, v82
	v_fma_f32 v187, v91, v94, v83
	v_fma_f32 v198, v92, v94, v84
	v_fma_f32 v199, v93, v94, v85
	v_mul_f32_e32 v78, v78, v186
	v_mul_f32_e32 v79, v79, v187
	s_waitcnt lgkmcnt(3)
	v_mul_f32_e32 v114, v114, v186
	v_mul_f32_e32 v115, v115, v187
	v_fmac_f32_e32 v78, v80, v198
	v_fmac_f32_e32 v79, v81, v199
	v_fmac_f32_e32 v114, v116, v198
	v_fmac_f32_e32 v115, v117, v199
	v_add_f32_e32 v188, v78, v79
	v_add_f32_e32 v114, v114, v115
	v_add_f32_dpp v62, v63, v63 row_mirror row_mask:0xf bank_mask:0xf bound_ctrl:1
	v_add_f32_dpp v115, v188, v188 quad_perm:[1,0,3,2] row_mask:0xf bank_mask:0xf bound_ctrl:1
	v_add_f32_dpp v114, v114, v114 quad_perm:[1,0,3,2] row_mask:0xf bank_mask:0xf bound_ctrl:1
	v_cndmask_b32_e64 v182, v64, v62, s[80:81]
	v_add_f32_dpp v115, v115, v115 quad_perm:[2,3,0,1] row_mask:0xf bank_mask:0xf bound_ctrl:1
	v_add_f32_dpp v114, v114, v114 quad_perm:[2,3,0,1] row_mask:0xf bank_mask:0xf bound_ctrl:1
	v_cndmask_b32_e64 v185, v182, v95, s[6:7]
	v_add_f32_dpp v115, v115, v115 row_half_mirror row_mask:0xf bank_mask:0xf bound_ctrl:1
	v_add_f32_dpp v114, v114, v114 row_half_mirror row_mask:0xf bank_mask:0xf bound_ctrl:1
	v_mul_f32_e32 v102, v102, v186
	v_mul_f32_e32 v103, v103, v187
	ds_read_b128 v[70:73], v195 offset:28224
	ds_read_b128 v[66:69], v195 offset:28480
	ds_read_b128 v[74:77], v195 offset:28736
	ds_read_b128 v[62:65], v195 offset:28992
	ds_read_b128 v[58:61], v195 offset:29248
	ds_read_b32 v0, v127 offset:29504
	v_add_f32_dpp v114, v114, v114 row_mirror row_mask:0xf bank_mask:0xf bound_ctrl:1
	v_add_f32_dpp v115, v115, v115 row_mirror row_mask:0xf bank_mask:0xf bound_ctrl:1
	s_waitcnt lgkmcnt(6)
	v_fmac_f32_e32 v102, v106, v184
	v_fmac_f32_e32 v103, v107, v184
	v_mul_f32_e32 v104, v104, v198
	v_mul_f32_e32 v105, v105, v199
	v_fma_f32 v186, v110, v114, v102
	v_fma_f32 v187, v111, v114, v103
	v_fmac_f32_e32 v104, v108, v184
	v_fmac_f32_e32 v105, v109, v184
	v_cndmask_b32_e64 v197, v185, v115, s[8:9]
	v_fma_f32 v184, v112, v114, v104
	v_fma_f32 v185, v113, v114, v105
	v_mul_f32_e32 v98, v98, v186
	v_mul_f32_e32 v99, v99, v187
	s_waitcnt lgkmcnt(3)
	v_mul_f32_e32 v74, v74, v186
	v_mul_f32_e32 v75, v75, v187
	v_fmac_f32_e32 v98, v100, v184
	v_fmac_f32_e32 v99, v101, v185
	v_fmac_f32_e32 v74, v76, v184
	v_fmac_f32_e32 v75, v77, v185
	v_add_f32_e32 v198, v98, v99
	v_add_f32_e32 v74, v74, v75
	v_mul_f32_e32 v70, v70, v186
	v_mul_f32_e32 v71, v71, v187
	v_add_f32_dpp v75, v198, v198 quad_perm:[1,0,3,2] row_mask:0xf bank_mask:0xf bound_ctrl:1
	v_add_f32_dpp v74, v74, v74 quad_perm:[1,0,3,2] row_mask:0xf bank_mask:0xf bound_ctrl:1
	s_waitcnt lgkmcnt(0)
	v_fma_f32 v66, v66, v0, v70
	v_fma_f32 v67, v67, v0, v71
	v_add_f32_dpp v75, v75, v75 quad_perm:[2,3,0,1] row_mask:0xf bank_mask:0xf bound_ctrl:1
	v_add_f32_dpp v74, v74, v74 quad_perm:[2,3,0,1] row_mask:0xf bank_mask:0xf bound_ctrl:1
	v_mul_f32_e32 v70, v72, v184
	v_mul_f32_e32 v71, v73, v185
	v_add_f32_dpp v75, v75, v75 row_half_mirror row_mask:0xf bank_mask:0xf bound_ctrl:1
	v_add_f32_dpp v74, v74, v74 row_half_mirror row_mask:0xf bank_mask:0xf bound_ctrl:1
	ds_read_b128 v[90:93], v195 offset:29568
	ds_read_b128 v[86:89], v195 offset:29824
	ds_read_b128 v[94:97], v195 offset:30080
	ds_read_b128 v[82:85], v195 offset:30336
	ds_read_b128 v[78:81], v195 offset:30592
	ds_read_b32 v182, v127 offset:30848
	v_add_f32_dpp v74, v74, v74 row_mirror row_mask:0xf bank_mask:0xf bound_ctrl:1
	v_add_f32_dpp v75, v75, v75 row_mirror row_mask:0xf bank_mask:0xf bound_ctrl:1
	v_fma_f32 v68, v68, v0, v70
	v_fma_f32 v69, v69, v0, v71
	v_fma_f32 v184, v62, v74, v66
	v_fma_f32 v185, v63, v74, v67
	v_fma_f32 v186, v64, v74, v68
	v_fma_f32 v187, v65, v74, v69
	v_mul_f32_e32 v58, v58, v184
	v_mul_f32_e32 v59, v59, v185
	s_waitcnt lgkmcnt(3)
	v_mul_f32_e32 v94, v94, v184
	v_mul_f32_e32 v95, v95, v185
	v_fmac_f32_e32 v58, v60, v186
	v_fmac_f32_e32 v59, v61, v187
	v_fmac_f32_e32 v94, v96, v186
	v_fmac_f32_e32 v95, v97, v187
	v_add_f32_e32 v198, v58, v59
	v_add_f32_e32 v94, v94, v95
	v_cndmask_b32_e64 v197, v197, v75, s[10:11]
	v_add_f32_dpp v95, v198, v198 quad_perm:[1,0,3,2] row_mask:0xf bank_mask:0xf bound_ctrl:1
	v_add_f32_dpp v94, v94, v94 quad_perm:[1,0,3,2] row_mask:0xf bank_mask:0xf bound_ctrl:1
	v_mul_f32_e32 v90, v90, v184
	v_mul_f32_e32 v91, v91, v185
	v_add_f32_dpp v95, v95, v95 quad_perm:[2,3,0,1] row_mask:0xf bank_mask:0xf bound_ctrl:1
	v_add_f32_dpp v94, v94, v94 quad_perm:[2,3,0,1] row_mask:0xf bank_mask:0xf bound_ctrl:1
	s_waitcnt lgkmcnt(0)
; #define LAS __attribute__((address_space(3)))
; template <int CTRL> __device__ __forceinline__ float dppf(float v) { return __int_as_float(__builtin_amdgcn_update_dpp(0, __float_as_int(v), CTRL, 0xf, 0xf, true)); }
; __device__ __forceinline__ void scan_phase(const Args& a, LAS unsigned char* lds, const bf16* Z, const float* W, const bf16* Aa, const bf16* KK, float* Y, int tid, int lane, int wave) {
;     ...
;                 for (int q = 0; q < SCH; ++q) {
;                     const f32x4 wv = pw[q % 3], kv = pk[q % 3], av = pa[q % 3], bv = pb[q % 3], rv = pr[q % 3]; const float vv = pv[q % 3];
;                     if (q + 2 < SCH) {
;                         const LAS float* p = sb + (q + 2) * SROW; const int i = (q + 2) % 3;
;                         pw[i] = *(const LAS f32x4*)p; pk[i] = *(const LAS f32x4*)(p + 64); pa[i] = *(const LAS f32x4*)(p + 128); pb[i] = *(const LAS f32x4*)(p + 192); pr[i] = *(const LAS f32x4*)(p + 256);
;                         pv[i] = vb[(q + 2) * SROW];
;                     }
;                     f32x2 t2 = S01 * (f32x2){av.x, av.y}; t2 = S23 * (f32x2){av.z, av.w} + t2;
;                     float sa = t2.x + t2.y;
;                     sa += dppf<0xB1>(sa); yd += dppf<0xB1>(yd);
;                     sa += dppf<0x4E>(sa); yd += dppf<0x4E>(yd);
;                     sa += dppf<0x141>(sa); yd += dppf<0x141>(yd);
;                     sa += dppf<0x140>(sa); yd += dppf<0x140>(yd);
;                     if (q > 0) { if (q <= 16) ykA = (j == q - 1) ? yd : ykA; else ykB = (j == q - 17) ? yd : ykB; }
;                     const f32x2 u01 = S01 * (f32x2){wv.x, wv.y} + (f32x2){kv.x, kv.y} * vv, u23 = S23 * (f32x2){wv.z, wv.w} + (f32x2){kv.z, kv.w} * vv;
;                     S01 = u01 + (f32x2){bv.x, bv.y} * sa; S23 = u23 + (f32x2){bv.z, bv.w} * sa;
;                     f32x2 y2 = S01 * (f32x2){rv.x, rv.y}; y2 = S23 * (f32x2){rv.z, rv.w} + y2;
;                     yd = y2.x + y2.y;
;                 }
	v_fma_f32 v86, v86, v182, v90
	v_fma_f32 v87, v87, v182, v91
	v_add_f32_dpp v95, v95, v95 row_half_mirror row_mask:0xf bank_mask:0xf bound_ctrl:1
	v_add_f32_dpp v94, v94, v94 row_half_mirror row_mask:0xf bank_mask:0xf bound_ctrl:1
	v_mul_f32_e32 v90, v92, v186
	v_mul_f32_e32 v91, v93, v187
	v_add_f32_dpp v95, v95, v95 row_mirror row_mask:0xf bank_mask:0xf bound_ctrl:1
	v_add_f32_dpp v94, v94, v94 row_mirror row_mask:0xf bank_mask:0xf bound_ctrl:1
	v_cndmask_b32_e64 v95, v197, v95, s[90:91]
	v_fma_f32 v88, v88, v182, v90
	v_fma_f32 v89, v89, v182, v91
	v_fma_f32 v82, v82, v94, v86
	v_fma_f32 v83, v83, v94, v87
	ds_read_b128 v[110:113], v195 offset:30912
	ds_read_b128 v[106:109], v195 offset:31168
	ds_read_b128 v[114:117], v195 offset:31424
	ds_read_b128 v[102:105], v195 offset:31680
	ds_read_b128 v[98:101], v195 offset:31936
	ds_read_b32 v188, v127 offset:32192
	v_fma_f32 v84, v84, v94, v88
	v_fma_f32 v85, v85, v94, v89
	v_mul_f32_e32 v78, v78, v82
	v_mul_f32_e32 v79, v79, v83
	ds_read_b128 v[58:61], v195 offset:32256
	ds_read_b128 v[62:65], v195 offset:32512
	ds_read_b128 v[66:69], v195 offset:32768
	ds_read_b128 v[70:73], v195 offset:33024
	ds_read_b128 v[74:77], v195 offset:33280
	ds_read_b32 v0, v127 offset:33536
	v_fmac_f32_e32 v78, v80, v84
	v_fmac_f32_e32 v79, v81, v85
	ds_read_b128 v[184:187], v195 offset:33600
	ds_read_b128 v[198:201], v195 offset:33856
	ds_read_b128 v[202:205], v195 offset:34112
	ds_read_b128 v[206:209], v195 offset:34368
	ds_read_b128 v[210:213], v195 offset:34624
	ds_read_b32 v182, v127 offset:34880
	v_add_f32_e32 v80, v78, v79
	s_waitcnt lgkmcnt(14)
	v_mul_f32_e32 v78, v114, v82
	v_mul_f32_e32 v79, v115, v83
	s_nop 0
	v_fmac_f32_e32 v78, v116, v84
	v_fmac_f32_e32 v79, v117, v85
	s_nop 0
	v_add_f32_e32 v78, v78, v79
	v_add_f32_dpp v79, v80, v80 quad_perm:[1,0,3,2] row_mask:0xf bank_mask:0xf bound_ctrl:1
	v_mul_f32_e32 v80, v110, v82
	v_mul_f32_e32 v81, v111, v83
	v_add_f32_dpp v78, v78, v78 quad_perm:[1,0,3,2] row_mask:0xf bank_mask:0xf bound_ctrl:1
	v_add_f32_dpp v79, v79, v79 quad_perm:[2,3,0,1] row_mask:0xf bank_mask:0xf bound_ctrl:1
	s_waitcnt lgkmcnt(12)
	v_fmac_f32_e32 v80, v106, v188
	v_fmac_f32_e32 v81, v107, v188
	v_add_f32_dpp v78, v78, v78 quad_perm:[2,3,0,1] row_mask:0xf bank_mask:0xf bound_ctrl:1
	v_add_f32_dpp v79, v79, v79 row_half_mirror row_mask:0xf bank_mask:0xf bound_ctrl:1
	v_mul_f32_e32 v82, v112, v84
	v_mul_f32_e32 v83, v113, v85
	v_add_f32_dpp v78, v78, v78 row_half_mirror row_mask:0xf bank_mask:0xf bound_ctrl:1
	v_add_f32_dpp v79, v79, v79 row_mirror row_mask:0xf bank_mask:0xf bound_ctrl:1
	v_fmac_f32_e32 v82, v108, v188
	v_fmac_f32_e32 v83, v109, v188
	v_add_f32_dpp v78, v78, v78 row_mirror row_mask:0xf bank_mask:0xf bound_ctrl:1
	v_fmac_f32_e32 v80, v102, v78
	v_fmac_f32_e32 v81, v103, v78
	v_cndmask_b32_e64 v86, v95, v79, s[60:61]
	v_fma_f32 v79, v105, v78, v83
	v_fma_f32 v78, v104, v78, v82
	v_mul_f32_e32 v82, v98, v80
	v_mul_f32_e32 v83, v99, v81
	s_waitcnt lgkmcnt(9)
	v_mul_f32_e32 v66, v66, v80
	v_mul_f32_e32 v67, v67, v81
	v_fmac_f32_e32 v82, v100, v78
	v_fmac_f32_e32 v83, v101, v79
	v_fmac_f32_e32 v66, v68, v78
	v_fmac_f32_e32 v67, v69, v79
	v_add_f32_e32 v82, v82, v83
	v_add_f32_e32 v66, v66, v67
	v_mul_f32_e32 v58, v58, v80
	v_mul_f32_e32 v59, v59, v81
	v_add_f32_dpp v67, v82, v82 quad_perm:[1,0,3,2] row_mask:0xf bank_mask:0xf bound_ctrl:1
	v_add_f32_dpp v66, v66, v66 quad_perm:[1,0,3,2] row_mask:0xf bank_mask:0xf bound_ctrl:1
	s_waitcnt lgkmcnt(6)
	v_fmac_f32_e32 v58, v62, v0
	v_fmac_f32_e32 v59, v63, v0
	v_add_f32_dpp v67, v67, v67 quad_perm:[2,3,0,1] row_mask:0xf bank_mask:0xf bound_ctrl:1
	v_add_f32_dpp v66, v66, v66 quad_perm:[2,3,0,1] row_mask:0xf bank_mask:0xf bound_ctrl:1
	v_mul_f32_e32 v60, v60, v78
	v_mul_f32_e32 v61, v61, v79
	v_add_f32_dpp v67, v67, v67 row_half_mirror row_mask:0xf bank_mask:0xf bound_ctrl:1
	v_add_f32_dpp v66, v66, v66 row_half_mirror row_mask:0xf bank_mask:0xf bound_ctrl:1
	v_fmac_f32_e32 v60, v64, v0
	v_fmac_f32_e32 v61, v65, v0
	v_add_f32_dpp v67, v67, v67 row_mirror row_mask:0xf bank_mask:0xf bound_ctrl:1
	v_add_f32_dpp v66, v66, v66 row_mirror row_mask:0xf bank_mask:0xf bound_ctrl:1
	v_cndmask_b32_e64 v67, v86, v67, s[62:63]
	v_fmac_f32_e32 v58, v70, v66
	v_fmac_f32_e32 v59, v71, v66
	v_fmac_f32_e32 v60, v72, v66
	v_fmac_f32_e32 v61, v73, v66
	v_mul_f32_e32 v62, v74, v58
	v_mul_f32_e32 v63, v75, v59
	ds_read_b128 v[218:221], v195 offset:34944
	ds_read_b128 v[222:225], v195 offset:35200
	ds_read_b128 v[226:229], v195 offset:35456
	ds_read_b128 v[230:233], v195 offset:35712
	ds_read_b128 v[234:237], v195 offset:35968
	ds_read_b32 v188, v127 offset:36224
	v_fmac_f32_e32 v62, v76, v60
	v_fmac_f32_e32 v63, v77, v61
	ds_read_b128 v[82:85], v195 offset:36288
	ds_read_b128 v[86:89], v195 offset:36544
	ds_read_b128 v[94:97], v195 offset:36800
	ds_read_b128 v[90:93], v195 offset:37056
	ds_read_b128 v[78:81], v195 offset:37312
	ds_read_b32 v214, v127 offset:37568
	v_add_f32_e32 v0, v62, v63
	s_waitcnt lgkmcnt(14)
	v_mul_f32_e32 v62, v202, v58
	v_mul_f32_e32 v63, v203, v59
	v_mul_f32_e32 v58, v184, v58
	v_mul_f32_e32 v59, v185, v59
	v_fmac_f32_e32 v62, v204, v60
	v_fmac_f32_e32 v63, v205, v61
	v_add_f32_dpp v0, v0, v0 quad_perm:[1,0,3,2] row_mask:0xf bank_mask:0xf bound_ctrl:1
	v_add_f32_e32 v62, v62, v63
	s_waitcnt lgkmcnt(12)
; #define LAS __attribute__((address_space(3)))
; template <int CTRL> __device__ __forceinline__ float dppf(float v) { return __int_as_float(__builtin_amdgcn_update_dpp(0, __float_as_int(v), CTRL, 0xf, 0xf, true)); }
; __device__ __forceinline__ void scan_phase(const Args& a, LAS unsigned char* lds, const bf16* Z, const float* W, const bf16* Aa, const bf16* KK, float* Y, int tid, int lane, int wave) {
;     ...
;                 for (int q = 0; q < SCH; ++q) {
;                     const f32x4 wv = pw[q % 3], kv = pk[q % 3], av = pa[q % 3], bv = pb[q % 3], rv = pr[q % 3]; const float vv = pv[q % 3];
;                     if (q + 2 < SCH) {
;                         const LAS float* p = sb + (q + 2) * SROW; const int i = (q + 2) % 3;
;                         pw[i] = *(const LAS f32x4*)p; pk[i] = *(const LAS f32x4*)(p + 64); pa[i] = *(const LAS f32x4*)(p + 128); pb[i] = *(const LAS f32x4*)(p + 192); pr[i] = *(const LAS f32x4*)(p + 256);
;                         pv[i] = vb[(q + 2) * SROW];
;                     }
;                     f32x2 t2 = S01 * (f32x2){av.x, av.y}; t2 = S23 * (f32x2){av.z, av.w} + t2;
;                     float sa = t2.x + t2.y;
;                     sa += dppf<0xB1>(sa); yd += dppf<0xB1>(yd);
;                     sa += dppf<0x4E>(sa); yd += dppf<0x4E>(yd);
;                     sa += dppf<0x141>(sa); yd += dppf<0x141>(yd);
;                     sa += dppf<0x140>(sa); yd += dppf<0x140>(yd);
;                     if (q > 0) { if (q <= 16) ykA = (j == q - 1) ? yd : ykA; else ykB = (j == q - 17) ? yd : ykB; }
;                     const f32x2 u01 = S01 * (f32x2){wv.x, wv.y} + (f32x2){kv.x, kv.y} * vv, u23 = S23 * (f32x2){wv.z, wv.w} + (f32x2){kv.z, kv.w} * vv;
;                     S01 = u01 + (f32x2){bv.x, bv.y} * sa; S23 = u23 + (f32x2){bv.z, bv.w} * sa;
;                     f32x2 y2 = S01 * (f32x2){rv.x, rv.y}; y2 = S23 * (f32x2){rv.z, rv.w} + y2;
;                     yd = y2.x + y2.y;
;                 }
	v_fmac_f32_e32 v58, v198, v182
	v_fmac_f32_e32 v59, v199, v182
	v_add_f32_dpp v0, v0, v0 quad_perm:[2,3,0,1] row_mask:0xf bank_mask:0xf bound_ctrl:1
	v_add_f32_dpp v62, v62, v62 quad_perm:[1,0,3,2] row_mask:0xf bank_mask:0xf bound_ctrl:1
	v_mul_f32_e32 v60, v186, v60
	v_mul_f32_e32 v61, v187, v61
	v_add_f32_dpp v63, v0, v0 row_half_mirror row_mask:0xf bank_mask:0xf bound_ctrl:1
	v_add_f32_dpp v62, v62, v62 quad_perm:[2,3,0,1] row_mask:0xf bank_mask:0xf bound_ctrl:1
	v_fmac_f32_e32 v60, v200, v182
	v_fmac_f32_e32 v61, v201, v182
	ds_read_b128 v[102:105], v195 offset:37632
	ds_read_b128 v[106:109], v195 offset:37888
	ds_read_b128 v[114:117], v195 offset:38144
	ds_read_b128 v[110:113], v195 offset:38400
	ds_read_b128 v[98:101], v195 offset:38656
	ds_read_b32 v184, v127 offset:38912
	v_add_f32_dpp v62, v62, v62 row_half_mirror row_mask:0xf bank_mask:0xf bound_ctrl:1
	s_nop 1
	v_add_f32_dpp v0, v62, v62 row_mirror row_mask:0xf bank_mask:0xf bound_ctrl:1
	v_add_f32_dpp v62, v63, v63 row_mirror row_mask:0xf bank_mask:0xf bound_ctrl:1
	v_fmac_f32_e32 v58, v206, v0
	v_fmac_f32_e32 v59, v207, v0
	v_cndmask_b32_e64 v64, v67, v62, s[64:65]
	v_fmac_f32_e32 v60, v208, v0
	v_fmac_f32_e32 v61, v209, v0
	v_mul_f32_e32 v62, v210, v58
	v_mul_f32_e32 v63, v211, v59
	s_nop 0
	v_fmac_f32_e32 v62, v212, v60
	v_fmac_f32_e32 v63, v213, v61
	s_nop 0
	v_add_f32_e32 v0, v62, v63
	s_waitcnt lgkmcnt(14)
	v_mul_f32_e32 v62, v226, v58
	v_mul_f32_e32 v63, v227, v59
	v_mul_f32_e32 v58, v218, v58
	v_mul_f32_e32 v59, v219, v59
	v_fmac_f32_e32 v62, v228, v60
	v_fmac_f32_e32 v63, v229, v61
	v_add_f32_dpp v0, v0, v0 quad_perm:[1,0,3,2] row_mask:0xf bank_mask:0xf bound_ctrl:1
	v_add_f32_e32 v62, v62, v63
	s_waitcnt lgkmcnt(12)
	v_fmac_f32_e32 v58, v222, v188
	v_fmac_f32_e32 v59, v223, v188
	v_add_f32_dpp v0, v0, v0 quad_perm:[2,3,0,1] row_mask:0xf bank_mask:0xf bound_ctrl:1
	v_add_f32_dpp v62, v62, v62 quad_perm:[1,0,3,2] row_mask:0xf bank_mask:0xf bound_ctrl:1
	v_mul_f32_e32 v60, v220, v60
	v_mul_f32_e32 v61, v221, v61
	v_add_f32_dpp v63, v0, v0 row_half_mirror row_mask:0xf bank_mask:0xf bound_ctrl:1
	v_add_f32_dpp v62, v62, v62 quad_perm:[2,3,0,1] row_mask:0xf bank_mask:0xf bound_ctrl:1
	v_fmac_f32_e32 v60, v224, v188
	v_fmac_f32_e32 v61, v225, v188
	s_nop 0
	v_add_f32_dpp v62, v62, v62 row_half_mirror row_mask:0xf bank_mask:0xf bound_ctrl:1
	s_nop 1
	v_add_f32_dpp v0, v62, v62 row_mirror row_mask:0xf bank_mask:0xf bound_ctrl:1
	v_fma_f32 v186, v230, v0, v58
	v_fma_f32 v187, v231, v0, v59
	v_fma_f32 v198, v232, v0, v60
	v_fma_f32 v199, v233, v0, v61
	v_mul_f32_e32 v58, v234, v186
	v_mul_f32_e32 v59, v235, v187
	s_waitcnt lgkmcnt(9)
	v_mul_f32_e32 v94, v94, v186
	v_mul_f32_e32 v95, v95, v187
	v_fmac_f32_e32 v58, v236, v198
	v_fmac_f32_e32 v59, v237, v199
	v_fmac_f32_e32 v94, v96, v198
	v_fmac_f32_e32 v95, v97, v199
	v_add_f32_e32 v185, v58, v59
	v_add_f32_e32 v94, v94, v95
	v_mul_f32_e32 v82, v82, v186
	v_mul_f32_e32 v83, v83, v187
	v_add_f32_dpp v95, v185, v185 quad_perm:[1,0,3,2] row_mask:0xf bank_mask:0xf bound_ctrl:1
	v_add_f32_dpp v94, v94, v94 quad_perm:[1,0,3,2] row_mask:0xf bank_mask:0xf bound_ctrl:1
	s_waitcnt lgkmcnt(6)
	v_fmac_f32_e32 v82, v86, v214
	v_fmac_f32_e32 v83, v87, v214
	v_add_f32_dpp v95, v95, v95 quad_perm:[2,3,0,1] row_mask:0xf bank_mask:0xf bound_ctrl:1
	v_add_f32_dpp v94, v94, v94 quad_perm:[2,3,0,1] row_mask:0xf bank_mask:0xf bound_ctrl:1
	v_mul_f32_e32 v84, v84, v198
	v_mul_f32_e32 v85, v85, v199
	v_add_f32_dpp v95, v95, v95 row_half_mirror row_mask:0xf bank_mask:0xf bound_ctrl:1
	v_add_f32_dpp v94, v94, v94 row_half_mirror row_mask:0xf bank_mask:0xf bound_ctrl:1
	v_fmac_f32_e32 v84, v88, v214
	v_fmac_f32_e32 v85, v89, v214
	v_add_f32_dpp v95, v95, v95 row_mirror row_mask:0xf bank_mask:0xf bound_ctrl:1
	v_add_f32_dpp v94, v94, v94 row_mirror row_mask:0xf bank_mask:0xf bound_ctrl:1
	v_fma_f32 v186, v90, v94, v82
	v_fma_f32 v187, v91, v94, v83
	v_fma_f32 v198, v92, v94, v84
	v_fma_f32 v199, v93, v94, v85
	v_mul_f32_e32 v78, v78, v186
	v_mul_f32_e32 v79, v79, v187
	s_waitcnt lgkmcnt(3)
	v_mul_f32_e32 v114, v114, v186
	v_mul_f32_e32 v115, v115, v187
	v_fmac_f32_e32 v78, v80, v198
	v_fmac_f32_e32 v79, v81, v199
	v_fmac_f32_e32 v114, v116, v198
	v_fmac_f32_e32 v115, v117, v199
	v_add_f32_e32 v188, v78, v79
	v_add_f32_e32 v114, v114, v115
	v_add_f32_dpp v62, v63, v63 row_mirror row_mask:0xf bank_mask:0xf bound_ctrl:1
	v_add_f32_dpp v115, v188, v188 quad_perm:[1,0,3,2] row_mask:0xf bank_mask:0xf bound_ctrl:1
	v_add_f32_dpp v114, v114, v114 quad_perm:[1,0,3,2] row_mask:0xf bank_mask:0xf bound_ctrl:1
	v_cndmask_b32_e64 v182, v64, v62, s[66:67]
	v_add_f32_dpp v115, v115, v115 quad_perm:[2,3,0,1] row_mask:0xf bank_mask:0xf bound_ctrl:1
	v_add_f32_dpp v114, v114, v114 quad_perm:[2,3,0,1] row_mask:0xf bank_mask:0xf bound_ctrl:1
	v_cndmask_b32_e64 v185, v182, v95, s[68:69]
	v_add_f32_dpp v115, v115, v115 row_half_mirror row_mask:0xf bank_mask:0xf bound_ctrl:1
	v_add_f32_dpp v114, v114, v114 row_half_mirror row_mask:0xf bank_mask:0xf bound_ctrl:1
	v_mul_f32_e32 v102, v102, v186
	v_mul_f32_e32 v103, v103, v187
	v_add_f32_dpp v115, v115, v115 row_mirror row_mask:0xf bank_mask:0xf bound_ctrl:1
	v_add_f32_dpp v114, v114, v114 row_mirror row_mask:0xf bank_mask:0xf bound_ctrl:1
	s_waitcnt lgkmcnt(0)
	v_fmac_f32_e32 v102, v106, v184
	v_fmac_f32_e32 v103, v107, v184
	v_mul_f32_e32 v104, v104, v198
	v_mul_f32_e32 v105, v105, v199
	ds_read_b128 v[70:73], v195 offset:38976
	ds_read_b128 v[66:69], v195 offset:39232
	ds_read_b128 v[74:77], v195 offset:39488
	ds_read_b128 v[62:65], v195 offset:39744
	ds_read_b128 v[58:61], v195 offset:40000
	ds_read_b32 v0, v127 offset:40256
	v_fmac_f32_e32 v104, v108, v184
	v_fmac_f32_e32 v105, v109, v184
	v_fma_f32 v186, v110, v114, v102
	v_fma_f32 v187, v111, v114, v103
	v_cndmask_b32_e64 v197, v185, v115, s[70:71]
	v_fma_f32 v184, v112, v114, v104
	v_fma_f32 v185, v113, v114, v105
	v_mul_f32_e32 v98, v98, v186
	v_mul_f32_e32 v99, v99, v187
	s_waitcnt lgkmcnt(3)
; #define LAS __attribute__((address_space(3)))
; template <int CTRL> __device__ __forceinline__ float dppf(float v) { return __int_as_float(__builtin_amdgcn_update_dpp(0, __float_as_int(v), CTRL, 0xf, 0xf, true)); }
; __device__ __forceinline__ float red16(float v) { v = red8(v); v += dppf<0x140>(v); return v; }
; __device__ __forceinline__ void scan_phase(const Args& a, LAS unsigned char* lds, const bf16* Z, const float* W, const bf16* Aa, const bf16* KK, float* Y, int tid, int lane, int wave) {
;     ...
;                 for (int q = 0; q < SCH; ++q) {
;                     const f32x4 wv = pw[q % 3], kv = pk[q % 3], av = pa[q % 3], bv = pb[q % 3], rv = pr[q % 3]; const float vv = pv[q % 3];
;                     if (q + 2 < SCH) {
;                         const LAS float* p = sb + (q + 2) * SROW; const int i = (q + 2) % 3;
;                         pw[i] = *(const LAS f32x4*)p; pk[i] = *(const LAS f32x4*)(p + 64); pa[i] = *(const LAS f32x4*)(p + 128); pb[i] = *(const LAS f32x4*)(p + 192); pr[i] = *(const LAS f32x4*)(p + 256);
;                         pv[i] = vb[(q + 2) * SROW];
;                     }
;                     f32x2 t2 = S01 * (f32x2){av.x, av.y}; t2 = S23 * (f32x2){av.z, av.w} + t2;
;                     float sa = t2.x + t2.y;
;                     sa += dppf<0xB1>(sa); yd += dppf<0xB1>(yd);
;                     sa += dppf<0x4E>(sa); yd += dppf<0x4E>(yd);
;                     sa += dppf<0x141>(sa); yd += dppf<0x141>(yd);
;                     sa += dppf<0x140>(sa); yd += dppf<0x140>(yd);
;                     if (q > 0) { if (q <= 16) ykA = (j == q - 1) ? yd : ykA; else ykB = (j == q - 17) ? yd : ykB; }
;                     const f32x2 u01 = S01 * (f32x2){wv.x, wv.y} + (f32x2){kv.x, kv.y} * vv, u23 = S23 * (f32x2){wv.z, wv.w} + (f32x2){kv.z, kv.w} * vv;
;                     S01 = u01 + (f32x2){bv.x, bv.y} * sa; S23 = u23 + (f32x2){bv.z, bv.w} * sa;
;                     f32x2 y2 = S01 * (f32x2){rv.x, rv.y}; y2 = S23 * (f32x2){rv.z, rv.w} + y2;
;                     yd = y2.x + y2.y;
;                 }
;                 yd = red16(yd); ykB = (j == 15) ? yd : ykB;
;                 yp[(size_t)(ch * SCH + j) * 512] = ykA;
;                 yp[(size_t)(ch * SCH + 16 + j) * 512] = ykB;
	v_mul_f32_e32 v74, v74, v186
	v_mul_f32_e32 v75, v75, v187
	v_fmac_f32_e32 v98, v100, v184
	v_fmac_f32_e32 v99, v101, v185
	v_fmac_f32_e32 v74, v76, v184
	v_fmac_f32_e32 v75, v77, v185
	v_add_f32_e32 v198, v98, v99
	v_add_f32_e32 v74, v74, v75
	v_mul_f32_e32 v70, v70, v186
	v_mul_f32_e32 v71, v71, v187
	v_add_f32_dpp v75, v198, v198 quad_perm:[1,0,3,2] row_mask:0xf bank_mask:0xf bound_ctrl:1
	v_add_f32_dpp v74, v74, v74 quad_perm:[1,0,3,2] row_mask:0xf bank_mask:0xf bound_ctrl:1
	s_waitcnt lgkmcnt(0)
	v_fma_f32 v66, v66, v0, v70
	v_fma_f32 v67, v67, v0, v71
	v_add_f32_dpp v75, v75, v75 quad_perm:[2,3,0,1] row_mask:0xf bank_mask:0xf bound_ctrl:1
	v_add_f32_dpp v74, v74, v74 quad_perm:[2,3,0,1] row_mask:0xf bank_mask:0xf bound_ctrl:1
	v_mul_f32_e32 v70, v72, v184
	v_mul_f32_e32 v71, v73, v185
	v_add_f32_dpp v75, v75, v75 row_half_mirror row_mask:0xf bank_mask:0xf bound_ctrl:1
	v_add_f32_dpp v74, v74, v74 row_half_mirror row_mask:0xf bank_mask:0xf bound_ctrl:1
	v_fma_f32 v68, v68, v0, v70
	v_fma_f32 v69, v69, v0, v71
	v_add_f32_dpp v75, v75, v75 row_mirror row_mask:0xf bank_mask:0xf bound_ctrl:1
	v_add_f32_dpp v74, v74, v74 row_mirror row_mask:0xf bank_mask:0xf bound_ctrl:1
	v_cndmask_b32_e64 v75, v197, v75, s[72:73]
	v_fma_f32 v62, v62, v74, v66
	v_fma_f32 v63, v63, v74, v67
	ds_read_b128 v[90:93], v195 offset:40320
	ds_read_b128 v[86:89], v195 offset:40576
	ds_read_b128 v[94:97], v195 offset:40832
	ds_read_b128 v[82:85], v195 offset:41088
	ds_read_b128 v[78:81], v195 offset:41344
	ds_read_b32 v182, v127 offset:41600
	v_fma_f32 v64, v64, v74, v68
	v_fma_f32 v65, v65, v74, v69
	v_mul_f32_e32 v58, v58, v62
	v_mul_f32_e32 v59, v59, v63
	ds_read_b128 v[110:113], v195 offset:41664
	ds_read_b128 v[106:109], v195 offset:41920
	ds_read_b128 v[114:117], v195 offset:42176
	ds_read_b128 v[102:105], v195 offset:42432
	ds_read_b128 v[98:101], v195 offset:42688
	ds_read_b32 v188, v127 offset:42944
	v_fmac_f32_e32 v58, v60, v64
	v_fmac_f32_e32 v59, v61, v65
	s_waitcnt lgkmcnt(11)
	v_mul_f32_e32 v60, v92, v64
	v_mul_f32_e32 v61, v93, v65
	v_add_f32_e32 v0, v58, v59
	s_waitcnt lgkmcnt(9)
	v_mul_f32_e32 v58, v94, v62
	v_mul_f32_e32 v59, v95, v63
	s_waitcnt lgkmcnt(6)
	v_fmac_f32_e32 v60, v88, v182
	v_fmac_f32_e32 v61, v89, v182
	v_fmac_f32_e32 v58, v96, v64
	v_fmac_f32_e32 v59, v97, v65
	v_add_f32_dpp v0, v0, v0 quad_perm:[1,0,3,2] row_mask:0xf bank_mask:0xf bound_ctrl:1
	v_add_f32_e32 v58, v58, v59
	s_nop 0
	v_add_f32_dpp v0, v0, v0 quad_perm:[2,3,0,1] row_mask:0xf bank_mask:0xf bound_ctrl:1
	v_add_f32_dpp v58, v58, v58 quad_perm:[1,0,3,2] row_mask:0xf bank_mask:0xf bound_ctrl:1
	s_nop 0
	v_add_f32_dpp v59, v0, v0 row_half_mirror row_mask:0xf bank_mask:0xf bound_ctrl:1
	v_add_f32_dpp v58, v58, v58 quad_perm:[2,3,0,1] row_mask:0xf bank_mask:0xf bound_ctrl:1
	s_nop 1
	v_add_f32_dpp v58, v58, v58 row_half_mirror row_mask:0xf bank_mask:0xf bound_ctrl:1
	s_nop 1
	v_add_f32_dpp v0, v58, v58 row_mirror row_mask:0xf bank_mask:0xf bound_ctrl:1
	v_add_f32_dpp v58, v59, v59 row_mirror row_mask:0xf bank_mask:0xf bound_ctrl:1
	v_cndmask_b32_e64 v66, v75, v58, s[74:75]
	v_mul_f32_e32 v58, v90, v62
	v_mul_f32_e32 v59, v91, v63
	v_fmac_f32_e32 v60, v84, v0
	v_fmac_f32_e32 v61, v85, v0
	v_fmac_f32_e32 v58, v86, v182
	v_fmac_f32_e32 v59, v87, v182
	s_nop 0
	v_fmac_f32_e32 v58, v82, v0
	v_fmac_f32_e32 v59, v83, v0
	s_nop 0
	v_mul_f32_e32 v62, v78, v58
	v_mul_f32_e32 v63, v79, v59
	s_nop 0
	v_fmac_f32_e32 v62, v80, v60
	v_fmac_f32_e32 v63, v81, v61
	s_nop 0
	v_add_f32_e32 v0, v62, v63
	s_waitcnt lgkmcnt(3)
	v_mul_f32_e32 v62, v114, v58
	v_mul_f32_e32 v63, v115, v59
	v_mul_f32_e32 v58, v110, v58
	v_mul_f32_e32 v59, v111, v59
	v_fmac_f32_e32 v62, v116, v60
	v_fmac_f32_e32 v63, v117, v61
	v_add_f32_dpp v0, v0, v0 quad_perm:[1,0,3,2] row_mask:0xf bank_mask:0xf bound_ctrl:1
	v_add_f32_e32 v62, v62, v63
	s_waitcnt lgkmcnt(0)
	v_fmac_f32_e32 v58, v106, v188
	v_fmac_f32_e32 v59, v107, v188
	v_add_f32_dpp v0, v0, v0 quad_perm:[2,3,0,1] row_mask:0xf bank_mask:0xf bound_ctrl:1
	v_add_f32_dpp v62, v62, v62 quad_perm:[1,0,3,2] row_mask:0xf bank_mask:0xf bound_ctrl:1
	v_mul_f32_e32 v60, v112, v60
	v_mul_f32_e32 v61, v113, v61
	v_add_f32_dpp v63, v0, v0 row_half_mirror row_mask:0xf bank_mask:0xf bound_ctrl:1
	v_add_f32_dpp v62, v62, v62 quad_perm:[2,3,0,1] row_mask:0xf bank_mask:0xf bound_ctrl:1
	v_fmac_f32_e32 v60, v108, v188
	v_fmac_f32_e32 v61, v109, v188
	s_nop 0
	v_add_f32_dpp v62, v62, v62 row_half_mirror row_mask:0xf bank_mask:0xf bound_ctrl:1
	s_nop 1
	v_add_f32_dpp v0, v62, v62 row_mirror row_mask:0xf bank_mask:0xf bound_ctrl:1
	v_add_f32_dpp v62, v63, v63 row_mirror row_mask:0xf bank_mask:0xf bound_ctrl:1
	v_fmac_f32_e32 v58, v102, v0
	v_fmac_f32_e32 v59, v103, v0
	v_cndmask_b32_e64 v64, v66, v62, s[76:77]
	v_fmac_f32_e32 v60, v104, v0
	v_fmac_f32_e32 v61, v105, v0
	v_mul_f32_e32 v62, v98, v58
	v_mul_f32_e32 v63, v99, v59
	s_nop 0
	v_fmac_f32_e32 v62, v100, v60
	v_fmac_f32_e32 v63, v101, v61
	s_nop 0
	v_add_f32_e32 v0, v62, v63
	v_lshl_add_u64 v[62:63], v[180:181], 0, s[4:5]
	s_nop 0
	v_add_f32_dpp v0, v0, v0 quad_perm:[1,0,3,2] row_mask:0xf bank_mask:0xf bound_ctrl:1
	s_nop 1
	v_add_f32_dpp v0, v0, v0 quad_perm:[2,3,0,1] row_mask:0xf bank_mask:0xf bound_ctrl:1
	s_nop 1
	v_add_f32_dpp v0, v0, v0 row_half_mirror row_mask:0xf bank_mask:0xf bound_ctrl:1
	s_nop 1
	v_add_f32_dpp v0, v0, v0 row_mirror row_mask:0xf bank_mask:0xf bound_ctrl:1
	v_cndmask_b32_e64 v0, v64, v0, s[96:97]
	v_add_co_u32_e32 v64, vcc, 0x5800000, v62
	s_nop 1
	v_addc_co_u32_e32 v65, vcc, 0, v63, vcc
	v_add_co_u32_e32 v62, vcc, 0x5808000, v62
	global_store_dword v[64:65], v196, off
	s_nop 0
	v_addc_co_u32_e32 v63, vcc, 0, v63, vcc
	global_store_dword v[62:63], v0, off
	s_branch .LBB0_224
